# adds next-unit RMS statistics prefetch in in-proj and gate-up epilogues (removes one exposed load round trip per unit)
# baseline (speedup 1.0000x reference)
; __device__ __forceinline__ int lane_id() { int l = __builtin_amdgcn_mbcnt_hi(~0u, __builtin_amdgcn_mbcnt_lo(~0u, 0u)); asm volatile("" : "+v"(l)); return l; }
; #define PG8_STAGE(bufoff, gbase, voff) do { _Pragma("unroll") for (int _i = 0; _i < 2; ++_i) \
;         __builtin_amdgcn_global_load_lds((const unsigned*)((const char*)(gbase) + (voff)[_i]), (LAS unsigned*)(lds + (bufoff) + ldsw + _i * 8192), 16, 0, 0); } while (0)
; #define PG8_BAR __builtin_amdgcn_s_barrier()
; template <int KK, class Epi, class Sched, bool ALIGN_EPI = true>
; __device__ __forceinline__ void gemm_phase(LAS unsigned char* lds, const bf16* gA, const bf16* gBt, const Sched& S, const Epi& E, const int wid) {
;     const int lane = lane_id();
;     const int tid = wid * 64 + lane, wr = wid >> 2, wc = wid & 3, fr = lane & 15, fq = lane >> 4;
;     constexpr int K = KK, nt = K / BK;
;     unsigned voffA[2], voffB[2];
; #pragma unroll
;     for (int i = 0; i < 2; ++i) { int R, C; stage_rc(tid * 16 + i * 8192, R, C); const int Rb = Epi::PERM ? ((R & ~31) + perm32(R & 31)) : R;
;         voffA[i] = (unsigned)(R * K + C) * 2u; voffB[i] = (unsigned)(Rb * K + C) * 2u; }
;     const size_t kstep = (size_t)(BK * 2);
;     const size_t hstep = (size_t)HALF * K * 2;
;     const size_t tstep = 2 * hstep;
;     const unsigned ldsw = (unsigned)wid * 1024u;
;     const int aoff = lds_byte(wr * 64 + fr, fq * 8), boff = lds_byte(wc * 32 + fr, fq * 8);
;     ...
;     Unit cur, nxt; int ui = 0;
;     if (!S.next(0, cur)) return;
;     f32x4 acc[2][2][4][2];
; #pragma unroll
;     for (int a = 0; a < 2; ++a)
; #pragma unroll
;         for (int b = 0; b < 2; ++b)
; #pragma unroll
;             for (int m = 0; m < 4; ++m)
; #pragma unroll
;                 for (int n = 0; n < 2; ++n) acc[a][b][m][n] = (f32x4){0.f, 0.f, 0.f, 0.f};
;     bf16x8 At[4][2], B0[2][2], B1[2][2];
;     const char* cA = (const char*)gA + (size_t)cur.pm * tstep; const char* cB = (const char*)gBt + (size_t)cur.pn * tstep;
;     PG8_STAGE(PG8_SB(0, 0), cB, voffB); PG8_STAGE(PG8_SB(0, 1), cB + hstep, voffB); PG8_STAGE(PG8_SA(0, 0), cA, voffA); PG8_STAGE(PG8_SA(0, 1), cA + hstep, voffA);
;     PG8_STAGE(PG8_SB(1, 0), cB + kstep, voffB); PG8_STAGE(PG8_SA(1, 0), cA + kstep, voffA); PG8_STAGE(PG8_SB(1, 1), cB + hstep + kstep, voffB);
;     if (wr == 1) PG8_BAR;
;     PG8_WAIT_V(8); PG8_BAR;
;     PG8_WAIT_V(6); PG8_BAR;
.LBB0_143:
	v_writelane_b32 v249, s8, 39
	s_bfe_u32 s0, s35, 0x20006
	s_nop 0
	v_writelane_b32 v249, s9, 40
	s_nop 0
	v_readlane_b32 s1, v249, 0
	s_lshl_b32 s33, s1, 10
	v_writelane_b32 v249, s35, 41
	s_lshr_b32 s1, s35, 8
	s_lshl_b32 s35, s1, 6
	v_writelane_b32 v249, s1, 42
	s_lshl_b32 s1, s1, 13
	v_writelane_b32 v249, s1, 43
	s_lshl_b32 s1, s0, 5
	v_writelane_b32 v249, s1, 44
	s_lshl_b32 s0, s0, 12
	v_writelane_b32 v249, s0, 45
	s_add_u32 s74, s44, 0x200000
	s_addc_u32 s75, s45, 0
	s_andn2_b64 vcc, exec, s[4:5]
	v_writelane_b32 v249, s38, 46
	s_nop 1
	v_writelane_b32 v249, s39, 47
	s_cbranch_vccnz .LBB0_290
	s_add_u32 s36, s44, 0x1000
	s_addc_u32 s37, s45, 0
	s_lshl_b32 s38, s84, 8
	s_add_i32 s38, s38, s35
	v_and_or_b32 v240, v196, 15, s38
	v_lshlrev_b32_e32 v240, 2, v240
	global_load_dword v232, v240, s[36:37]
	global_load_dword v233, v240, s[36:37] offset:64
	global_load_dword v234, v240, s[36:37] offset:128
	global_load_dword v235, v240, s[36:37] offset:192
	global_load_dword v236, v240, s[36:37] offset:512
	global_load_dword v237, v240, s[36:37] offset:576
	global_load_dword v238, v240, s[36:37] offset:640
	global_load_dword v239, v240, s[36:37] offset:704
	v_lshlrev_b32_e32 v4, 4, v0
	v_add_u32_e32 v5, s33, v4
	v_ashrrev_i32_e32 v1, 31, v5
	v_lshrrev_b32_e32 v1, 22, v1
	v_add_u32_e32 v1, v5, v1
	v_ashrrev_i32_e32 v1, 10, v1
	v_mul_i32_i24_e32 v2, 0x400, v1
	v_sub_u32_e32 v2, v5, v2
	v_lshrrev_b32_e32 v3, 4, v2
	v_bitop3_b32 v3, v3, v2, 32 bitop3:0x6c
	v_lshlrev_b32_e32 v2, 3, v1
	v_and_b32_e32 v6, -16, v2
	v_ashrrev_i32_e32 v2, 31, v3
	v_lshrrev_b32_e32 v2, 26, v2
	v_add_u32_e32 v7, v3, v2
	v_ashrrev_i32_e32 v2, 6, v7
	v_and_b32_e32 v7, 0xc0, v7
	v_sub_u32_e32 v3, v3, v7
	v_mov_b32_e32 v7, 1
	v_lshlrev_b32_e32 v8, 5, v1
	v_ashrrev_i16_sdwa v3, v7, sext(v3) dst_sel:DWORD dst_unused:UNUSED_PAD src0_sel:DWORD src1_sel:BYTE_0
	v_and_b32_e32 v8, 32, v8
	v_bfe_i32 v3, v3, 0, 16
	v_add_u32_e32 v6, v2, v6
	v_and_b32_e32 v11, 3, v2
	s_mov_b32 s0, 0x1fffe0
	v_add_lshl_u32 v8, v8, v3, 1
	v_lshlrev_b32_e32 v9, 1, v6
	v_lshrrev_b32_e32 v10, 2, v6
	v_and_or_b32 v11, v6, s0, v11
	v_lshl_add_u32 v128, v6, 11, v8
	v_add_u32_e32 v6, 0x2000, v5
	v_ashrrev_i32_e32 v5, 31, v6
	v_lshrrev_b32_e32 v5, 22, v5
	v_and_b32_e32 v9, 24, v9
	v_and_b32_e32 v10, 4, v10
	v_add_u32_e32 v5, v6, v5
	v_or3_b32 v9, v11, v10, v9
	v_ashrrev_i32_e32 v5, 10, v5
	v_lshl_add_u32 v130, v9, 11, v8
	v_mul_i32_i24_e32 v8, 0x400, v5
	v_sub_u32_e32 v6, v6, v8
	v_lshrrev_b32_e32 v8, 4, v6
	v_bitop3_b32 v8, v8, v6, 32 bitop3:0x6c
	v_lshlrev_b32_e32 v6, 3, v5
	v_and_b32_e32 v9, -16, v6
	v_ashrrev_i32_e32 v6, 31, v8
	v_lshrrev_b32_e32 v6, 26, v6
	v_add_u32_e32 v10, v8, v6
	v_ashrrev_i32_e32 v6, 6, v10
	v_and_b32_e32 v10, 0xffc0, v10
	v_sub_u32_e32 v8, v8, v10
	s_add_u32 s69, s44, 0x3600000
	v_add_u32_e32 v9, v6, v9
	v_lshrrev_b16_e32 v10, 7, v8
	v_and_b32_e32 v12, 3, v6
	s_addc_u32 s76, s45, 0
	s_ashr_i32 s85, s84, 31
	s_ashr_i32 s13, s12, 31
	v_and_b32_e32 v10, 1, v10
	v_and_or_b32 v12, v9, s0, v12
	s_lshl_b64 s[0:1], s[84:85], 19
	s_lshl_b64 s[2:3], s[12:13], 19
	v_add_u16_e32 v8, v8, v10
	s_add_u32 s4, s74, s2
	v_lshlrev_b32_e32 v11, 5, v5
	v_ashrrev_i16_sdwa v7, v7, sext(v8) dst_sel:DWORD dst_unused:UNUSED_PAD src0_sel:DWORD src1_sel:BYTE_0
	v_lshlrev_b32_e32 v8, 1, v9
	v_lshrrev_b32_e32 v10, 2, v9
	s_addc_u32 s5, s75, s3
	s_add_i32 s77, s33, 0
	v_and_b32_e32 v11, 32, v11
	v_bfe_i32 v7, v7, 0, 16
	v_and_b32_e32 v8, 24, v8
	v_and_b32_e32 v10, 4, v10
	s_add_i32 m0, s77, 0x10000
	v_or3_b32 v8, v12, v10, v8
	v_add_lshl_u32 v10, v11, v7, 1
	global_load_lds_dwordx4 v130, s[4:5]
	s_add_i32 m0, s77, 0x12000
	v_lshl_add_u32 v134, v8, 11, v10
	s_add_u32 s2, s4, 0x40000
	global_load_lds_dwordx4 v134, s[4:5]
	s_addc_u32 s3, s5, 0
	s_add_i32 m0, s77, 0x14000
	v_lshl_add_u32 v132, v9, 11, v10
	global_load_lds_dwordx4 v130, s[2:3]
	s_add_i32 m0, s77, 0x16000
	s_add_u32 s6, s69, s0
	s_addc_u32 s7, s76, s1
	s_add_i32 s62, s77, 0x2000
	global_load_lds_dwordx4 v134, s[2:3]
	s_mov_b32 m0, s77
	s_add_u32 s2, s6, 0x40000
	v_mov_b32_e32 v137, 0
	global_load_lds_dwordx4 v128, s[6:7]
	s_mov_b32 m0, s62
	s_addc_u32 s3, s7, 0
	s_add_i32 s0, s77, 0x4000
	v_mov_b32_e32 v131, v137
	global_load_lds_dwordx4 v132, s[6:7]
	s_mov_b32 m0, s0
	s_add_i32 s1, s77, 0x6000
	v_lshl_add_u64 v[8:9], s[4:5], 0, v[130:131]
	v_mov_b32_e32 v135, v137
	global_load_lds_dwordx4 v128, s[2:3]
	s_mov_b32 m0, s1
	s_mov_b64 s[40:41], 0x80
	v_lshl_add_u64 v[10:11], s[4:5], 0, v[134:135]
	v_mov_b32_e32 v129, v137
	global_load_lds_dwordx4 v132, s[2:3]
	s_add_i32 m0, s77, 0x18000
	v_lshl_add_u64 v[8:9], v[8:9], 0, s[40:41]
	v_lshl_add_u64 v[12:13], s[6:7], 0, v[128:129]
	v_mov_b32_e32 v133, v137
	global_load_lds_dwordx4 v[8:9], off
	v_lshl_add_u64 v[8:9], v[10:11], 0, s[40:41]
	s_add_i32 m0, s77, 0x1a000
	s_add_i32 s63, s77, 0x8000
	v_lshl_add_u64 v[14:15], s[6:7], 0, v[132:133]
	global_load_lds_dwordx4 v[8:9], off
	v_lshl_add_u64 v[8:9], v[12:13], 0, s[40:41]
	s_mov_b32 m0, s63
	s_add_i32 s68, s77, 0xa000
	global_load_lds_dwordx4 v[8:9], off
	v_lshl_add_u64 v[8:9], v[14:15], 0, s[40:41]
	s_mov_b32 m0, s68
	s_add_u32 s2, s4, 0x40080
	global_load_lds_dwordx4 v[8:9], off
	s_addc_u32 s3, s5, 0
	s_add_i32 m0, s77, 0x1c000
	v_writelane_b32 v249, s28, 48
	global_load_lds_dwordx4 v130, s[2:3]
	s_add_i32 m0, s77, 0x1e000
	v_writelane_b32 v249, s29, 49
	global_load_lds_dwordx4 v134, s[2:3]
	v_readlane_b32 s2, v249, 42
	s_cmp_eq_u32 s2, 1
	s_cselect_b64 s[8:9], -1, 0
	v_writelane_b32 v249, s8, 50
	s_cmp_lg_u32 s2, 1
	s_mov_b32 s85, 0
	v_writelane_b32 v249, s9, 51
	s_cbranch_scc1 .LBB0_146
	s_barrier

;     __device__ __forceinline__ void operator()(AccRef acc, const pg8::Unit& u, int wr, int wc, int, int) const {
;     ...
;         float sq[2][4];
; #pragma unroll
;         for (int ai = 0; ai < 2; ++ai)
; #pragma unroll
;             for (int m = 0; m < 4; ++m) sq[ai][m] = ssq[pm * 256 + ai * 128 + wr * 64 + m * 16 + fr];
;         asm volatile("" ::: "memory");
; #pragma unroll
;         for (int ai = 0; ai < 2; ++ai)
; #pragma unroll
;             for (int m = 0; m < 4; ++m) {
;                 const int row = pm * 256 + ai * 128 + wr * 64 + m * 16 + fr;
;                 const float rstd = __builtin_amdgcn_rsqf(sq[ai][m] * (1.0f / DM) + EPS) * (isq ? QSCALE : 1.0f);
;                 const int pos = samp ? 2048 + ((row - MP) & 63) : (row & 16383);
; #pragma unroll
;                 for (int bj = 0; bj < 2; ++bj) {
;                     const int c0 = pn * 256 + bj * 128 + wc * 32 + 8 * fq;
;                     float v[8];
; #pragma unroll
;                     for (int j = 0; j < 4; ++j) { v[j] = acc[ai][bj][m][0][j] * rstd; v[4 + j] = acc[ai][bj][m][1][j] * rstd; }
;                     const bool ropet = (pn == 6 || pn == 7 || (pn == 8 && bj == 0)) && ((wc & 1) == 0);
;                     if (ropet) {
;                         float pv[8];
; #pragma unroll
;                         for (int j = 0; j < 8; ++j) pv[j] = __shfl_xor(v[j], 16);
;                         if (fq < 2) {
;                             const f32x4* cs = (const f32x4*)(rope + (size_t)pos * 16);
;                             const float sg = (fq == 0) ? -1.f : 1.f;
; #pragma unroll
;                             for (int jj = 0; jj < 4; ++jj) { const f32x4 t = cs[jj];
;                                 v[2 * jj] = v[2 * jj] * t[0] + sg * pv[2 * jj] * t[1];
.LBB0_158:
	s_mov_b64 s[8:9], s[44:45]
	s_mov_b64 s[94:95], s[46:47]
	s_add_u32 s6, s8, 0x1000
	s_addc_u32 s7, s9, 0
	s_cmpk_gt_i32 s84, 0x7f
	s_cselect_b64 s[4:5], -1, 0
	s_cmp_lt_i32 s12, 2
	s_cselect_b64 s[10:11], -1, 0
	s_and_b32 s13, s12, -2
	s_cmp_eq_u32 s13, 6
	v_mov_b32_e32 v136, v196
	s_cselect_b64 s[56:57], -1, 0
	s_lshl_b32 s53, s84, 8
	s_add_i32 s53, s53, s35
	v_and_b32_e32 v177, 15, v136
	v_or_b32_e32 v144, s53, v177
	v_ashrrev_i32_e32 v145, 31, v144
	v_or_b32_e32 v154, 16, v144
	v_lshl_add_u64 v[146:147], v[144:145], 2, s[6:7]
	v_ashrrev_i32_e32 v155, 31, v154
	v_or_b32_e32 v152, 32, v144
	v_mov_b32_e32 v148, v232
	v_lshl_add_u64 v[146:147], v[154:155], 2, s[6:7]
	v_ashrrev_i32_e32 v153, 31, v152
	v_or_b32_e32 v150, 48, v144
	v_mov_b32_e32 v182, v233
	v_lshl_add_u64 v[146:147], v[152:153], 2, s[6:7]
	v_ashrrev_i32_e32 v151, 31, v150
	v_mov_b32_e32 v181, v234
	v_lshl_add_u64 v[146:147], v[150:151], 2, s[6:7]
	v_mov_b32_e32 v180, v235
	v_add_u32_e32 v146, 0x80, v144
	v_ashrrev_i32_e32 v147, 31, v146
	v_lshl_add_u64 v[146:147], v[146:147], 2, s[6:7]
	v_mov_b32_e32 v178, v236
	v_add_u32_e32 v146, 0x90, v144
	v_ashrrev_i32_e32 v147, 31, v146
	v_lshl_add_u64 v[146:147], v[146:147], 2, s[6:7]
	v_mov_b32_e32 v176, v237
	v_add_u32_e32 v146, 0xa0, v144
	v_ashrrev_i32_e32 v147, 31, v146
	v_lshl_add_u64 v[146:147], v[146:147], 2, s[6:7]
	v_mov_b32_e32 v155, v238
	v_add_u32_e32 v146, 0xb0, v144
	v_ashrrev_i32_e32 v147, 31, v146
	v_lshl_add_u64 v[146:147], v[146:147], 2, s[6:7]
	v_mov_b32_e32 v153, v239
	s_or_b64 vcc, s[10:11], s[56:57]
	v_ashrrev_i32_e32 v145, 4, v136
	v_cndmask_b32_e32 v151, 1.0, v175, vcc
	v_cmp_gt_u32_e32 vcc, 16, v136
	s_add_u32 s96, s8, 0x100000
	s_addc_u32 s97, s9, 0
	s_add_i32 s10, s12, -6
	v_or_b32_e32 v179, 0x800, v177
	s_cmp_lt_u32 s10, 3
	s_cselect_b64 s[10:11], -1, 0
	s_and_b64 s[14:15], s[78:79], s[10:11]
	v_cmp_gt_i32_e64 s[6:7], 2, v145
	v_cndmask_b32_e64 v142, 1.0, -1.0, vcc
	s_andn2_b64 vcc, exec, s[14:15]
	s_cmp_lg_u64 s[88:89], 0
	s_cbranch_scc0 .Lp1aq_nopf
	s_add_u32 s36, s44, 0x1000
	s_addc_u32 s37, s45, 0
	s_lshl_b32 s38, s52, 8
	s_add_i32 s38, s38, s35
	v_and_or_b32 v240, v196, 15, s38
	v_lshlrev_b32_e32 v240, 2, v240
	global_load_dword v232, v240, s[36:37]
	global_load_dword v233, v240, s[36:37] offset:64
	global_load_dword v234, v240, s[36:37] offset:128
	global_load_dword v235, v240, s[36:37] offset:192
	global_load_dword v236, v240, s[36:37] offset:512
	global_load_dword v237, v240, s[36:37] offset:576
	global_load_dword v238, v240, s[36:37] offset:640
	global_load_dword v239, v240, s[36:37] offset:704
.Lp1aq_nopf:
	v_fmamk_f32 v136, v148, 0x3a800000, v174
	v_rsq_f32_e32 v136, v136
	s_nop 0
	v_mul_f32_e32 v156, v151, v136
	v_mov_b32_e32 v136, s53
	v_bitop3_b32 v157, v177, s70, v136 bitop3:0xc8
	v_cndmask_b32_e64 v136, v157, v179, s[4:5]
	v_lshlrev_b32_e32 v136, 6, v136
	v_lshl_add_u64 v[158:159], s[96:97], 0, v[136:137]
	v_cndmask_b32_e64 v136, 0, 1, s[14:15]
	v_pk_mul_f32 v[124:125], v[124:125], v[156:157] op_sel_hi:[1,0]
	v_pk_mul_f32 v[120:121], v[120:121], v[156:157] op_sel_hi:[1,0]
	v_pk_mul_f32 v[126:127], v[126:127], v[156:157] op_sel_hi:[1,0]
	v_pk_mul_f32 v[122:123], v[122:123], v[156:157] op_sel_hi:[1,0]
	v_cmp_ne_u32_e64 s[10:11], 1, v136
	s_cbranch_vccnz .LBB0_162
	ds_bpermute_b32 v160, v168, v124
	ds_bpermute_b32 v161, v168, v125
	ds_bpermute_b32 v148, v168, v126
	ds_bpermute_b32 v149, v168, v127
	ds_bpermute_b32 v146, v168, v120
	ds_bpermute_b32 v147, v168, v121
	ds_bpermute_b32 v162, v168, v122
	ds_bpermute_b32 v136, v168, v123
	s_and_saveexec_b64 s[14:15], s[6:7]
	s_cbranch_execz .LBB0_161
	global_load_dwordx4 v[184:187], v[158:159], off offset:48
	global_load_dwordx4 v[188:191], v[158:159], off offset:32
	global_load_dwordx4 v[192:195], v[158:159], off offset:16
	global_load_dwordx4 v[198:201], v[158:159], off
	s_waitcnt lgkmcnt(1)
	v_mul_f32_e32 v162, v142, v162
	v_pk_mul_f32 v[160:161], v[142:143], v[160:161] op_sel_hi:[0,1]
	v_pk_mul_f32 v[148:149], v[142:143], v[148:149] op_sel_hi:[0,1]
	v_pk_mul_f32 v[146:147], v[142:143], v[146:147] op_sel_hi:[0,1]
	s_waitcnt vmcnt(3)
	v_mul_f32_e32 v122, v122, v184
	v_mul_f32_e32 v162, v162, v185
	s_waitcnt vmcnt(0)
	v_mov_b32_e32 v164, v198
	v_mov_b32_e32 v165, v200
	v_pk_mul_f32 v[124:125], v[124:125], v[164:165]
	v_mov_b32_e32 v164, v192
	v_mov_b32_e32 v165, v194
	v_pk_mul_f32 v[126:127], v[126:127], v[164:165]
	v_mov_b32_e32 v164, v188
	v_mov_b32_e32 v165, v190
	v_pk_mul_f32 v[120:121], v[120:121], v[164:165]
	s_waitcnt lgkmcnt(0)
	v_mul_f32_e32 v165, v142, v136
	v_mov_b32_e32 v164, v123
	v_pk_mul_f32 v[164:165], v[164:165], v[186:187]
	v_mov_b32_e32 v200, v199
	v_mov_b32_e32 v194, v193
	v_mov_b32_e32 v190, v189
	v_mov_b32_e32 v123, v165
	v_mov_b32_e32 v163, v164
	v_pk_fma_f32 v[124:125], v[160:161], v[200:201], v[124:125]
	v_pk_fma_f32 v[126:127], v[148:149], v[194:195], v[126:127]
	v_pk_fma_f32 v[120:121], v[146:147], v[190:191], v[120:121]
	v_pk_add_f32 v[122:123], v[122:123], v[162:163]

; __device__ __forceinline__ int lane_id() { int l = __builtin_amdgcn_mbcnt_hi(~0u, __builtin_amdgcn_mbcnt_lo(~0u, 0u)); asm volatile("" : "+v"(l)); return l; }
; #define PG8_STAGE(bufoff, gbase, voff) do { _Pragma("unroll") for (int _i = 0; _i < 2; ++_i) \
;         __builtin_amdgcn_global_load_lds((const unsigned*)((const char*)(gbase) + (voff)[_i]), (LAS unsigned*)(lds + (bufoff) + ldsw + _i * 8192), 16, 0, 0); } while (0)
; #define PG8_BAR __builtin_amdgcn_s_barrier()
; template <int KK, class Epi, class Sched, bool ALIGN_EPI = true>
; __device__ __forceinline__ void gemm_phase(LAS unsigned char* lds, const bf16* gA, const bf16* gBt, const Sched& S, const Epi& E, const int wid) {
;     const int lane = lane_id();
;     const int tid = wid * 64 + lane, wr = wid >> 2, wc = wid & 3, fr = lane & 15, fq = lane >> 4;
;     constexpr int K = KK, nt = K / BK;
;     unsigned voffA[2], voffB[2];
; #pragma unroll
;     for (int i = 0; i < 2; ++i) { int R, C; stage_rc(tid * 16 + i * 8192, R, C); const int Rb = Epi::PERM ? ((R & ~31) + perm32(R & 31)) : R;
;         voffA[i] = (unsigned)(R * K + C) * 2u; voffB[i] = (unsigned)(Rb * K + C) * 2u; }
;     const size_t kstep = (size_t)(BK * 2);
;     const size_t hstep = (size_t)HALF * K * 2;
;     const size_t tstep = 2 * hstep;
;     const unsigned ldsw = (unsigned)wid * 1024u;
;     const int aoff = lds_byte(wr * 64 + fr, fq * 8), boff = lds_byte(wc * 32 + fr, fq * 8);
;     ...
;     Unit cur, nxt; int ui = 0;
;     if (!S.next(0, cur)) return;
;     f32x4 acc[2][2][4][2];
; #pragma unroll
;     for (int a = 0; a < 2; ++a)
; #pragma unroll
;         for (int b = 0; b < 2; ++b)
; #pragma unroll
;             for (int m = 0; m < 4; ++m)
; #pragma unroll
;                 for (int n = 0; n < 2; ++n) acc[a][b][m][n] = (f32x4){0.f, 0.f, 0.f, 0.f};
;     bf16x8 At[4][2], B0[2][2], B1[2][2];
;     const char* cA = (const char*)gA + (size_t)cur.pm * tstep; const char* cB = (const char*)gBt + (size_t)cur.pn * tstep;
;     PG8_STAGE(PG8_SB(0, 0), cB, voffB); PG8_STAGE(PG8_SB(0, 1), cB + hstep, voffB); PG8_STAGE(PG8_SA(0, 0), cA, voffA); PG8_STAGE(PG8_SA(0, 1), cA + hstep, voffA);
;     PG8_STAGE(PG8_SB(1, 0), cB + kstep, voffB); PG8_STAGE(PG8_SA(1, 0), cA + kstep, voffA); PG8_STAGE(PG8_SB(1, 1), cB + hstep + kstep, voffB);
;     if (wr == 1) PG8_BAR;
;     PG8_WAIT_V(8); PG8_BAR;
;     PG8_WAIT_V(6); PG8_BAR;
.LBB0_598:
	s_add_u32 s84, s44, 0x22000
	s_addc_u32 s85, s45, 0
	s_lshl_b32 s83, s58, 8
	s_add_i32 s83, s83, s35
	v_and_or_b32 v240, v196, 15, s83
	v_lshlrev_b32_e32 v240, 2, v240
	global_load_dword v232, v240, s[84:85]
	global_load_dword v233, v240, s[84:85] offset:64
	global_load_dword v234, v240, s[84:85] offset:128
	global_load_dword v235, v240, s[84:85] offset:192
	global_load_dword v236, v240, s[84:85] offset:512
	global_load_dword v237, v240, s[84:85] offset:576
	global_load_dword v238, v240, s[84:85] offset:640
	global_load_dword v239, v240, s[84:85] offset:704
	v_lshl_add_u32 v4, v0, 4, s33
	v_ashrrev_i32_e32 v1, 31, v4
	v_lshrrev_b32_e32 v1, 22, v1
	v_add_u32_e32 v1, v4, v1
	v_ashrrev_i32_e32 v1, 10, v1
	v_mul_i32_i24_e32 v2, 0x400, v1
	v_sub_u32_e32 v2, v4, v2
	v_lshrrev_b32_e32 v3, 4, v2
	v_bitop3_b32 v3, v3, v2, 32 bitop3:0x6c
	v_lshlrev_b32_e32 v2, 3, v1
	v_and_b32_e32 v5, -16, v2
	v_ashrrev_i32_e32 v2, 31, v3
	v_lshrrev_b32_e32 v2, 26, v2
	v_add_u32_e32 v6, v3, v2
	v_ashrrev_i32_e32 v2, 6, v6
	v_and_b32_e32 v6, 0xc0, v6
	v_sub_u32_e32 v3, v3, v6
	v_mov_b32_e32 v6, 1
	v_lshlrev_b32_e32 v7, 5, v1
	v_ashrrev_i16_sdwa v3, v6, sext(v3) dst_sel:DWORD dst_unused:UNUSED_PAD src0_sel:DWORD src1_sel:BYTE_0
	v_and_b32_e32 v7, 32, v7
	v_bfe_i32 v3, v3, 0, 16
	v_add_u32_e32 v5, v2, v5
	v_and_b32_e32 v10, 3, v2
	s_mov_b32 s6, 0x1fffe0
	v_add_lshl_u32 v7, v7, v3, 1
	v_lshlrev_b32_e32 v8, 1, v5
	v_lshrrev_b32_e32 v9, 2, v5
	v_and_or_b32 v10, v5, s6, v10
	v_lshl_add_u32 v128, v5, 11, v7
	v_add_u32_e32 v5, 0x2000, v4
	v_ashrrev_i32_e32 v4, 31, v5
	v_lshrrev_b32_e32 v4, 22, v4
	v_and_b32_e32 v8, 24, v8
	v_and_b32_e32 v9, 4, v9
	v_add_u32_e32 v4, v5, v4
	v_or3_b32 v8, v10, v9, v8
	v_ashrrev_i32_e32 v4, 10, v4
	v_lshl_add_u32 v130, v8, 11, v7
	v_mul_i32_i24_e32 v7, 0x400, v4
	v_sub_u32_e32 v5, v5, v7
	v_lshrrev_b32_e32 v7, 4, v5
	v_bitop3_b32 v7, v7, v5, 32 bitop3:0x6c
	v_lshlrev_b32_e32 v5, 3, v4
	v_and_b32_e32 v8, -16, v5
	v_ashrrev_i32_e32 v5, 31, v7
	v_lshrrev_b32_e32 v5, 26, v5
	v_add_u32_e32 v9, v7, v5
	v_ashrrev_i32_e32 v5, 6, v9
	v_and_b32_e32 v9, 0xffc0, v9
	s_add_u32 s2, s44, 0x880000
	v_sub_u32_e32 v7, v7, v9
	s_addc_u32 s3, s45, 0
	v_add_u32_e32 v8, v5, v8
	v_lshrrev_b16_e32 v9, 7, v7
	v_and_b32_e32 v11, 3, v5
	s_ashr_i32 s59, s58, 31
	s_ashr_i32 s57, s56, 31
	v_and_b32_e32 v9, 1, v9
	v_and_or_b32 v11, v8, s6, v11
	s_lshl_b64 s[6:7], s[58:59], 19
	s_lshl_b64 s[10:11], s[56:57], 19
	v_add_u16_e32 v7, v7, v9
	s_add_u32 s66, s2, s10
	v_lshlrev_b32_e32 v10, 5, v4
	v_ashrrev_i16_sdwa v6, v6, sext(v7) dst_sel:DWORD dst_unused:UNUSED_PAD src0_sel:DWORD src1_sel:BYTE_0
	v_lshlrev_b32_e32 v7, 1, v8
	v_lshrrev_b32_e32 v9, 2, v8
	s_addc_u32 s67, s3, s11
	s_add_i32 s29, s33, 0
	v_and_b32_e32 v10, 32, v10
	v_bfe_i32 v6, v6, 0, 16
	v_and_b32_e32 v7, 24, v7
	v_and_b32_e32 v9, 4, v9
	s_add_i32 m0, s29, 0x10000
	v_or3_b32 v7, v11, v9, v7
	v_add_lshl_u32 v9, v10, v6, 1
	global_load_lds_dwordx4 v130, s[66:67]
	s_add_i32 m0, s29, 0x12000
	v_lshl_add_u32 v134, v7, 11, v9
	s_add_u32 s10, s66, 0x40000
	global_load_lds_dwordx4 v134, s[66:67]
	s_addc_u32 s11, s67, 0
	s_add_i32 m0, s29, 0x14000
	v_lshl_add_u32 v132, v8, 11, v9
	global_load_lds_dwordx4 v130, s[10:11]
	s_add_i32 m0, s29, 0x16000
	s_add_u32 s76, s9, s6
	s_addc_u32 s77, s5, s7
	s_add_i32 s40, s29, 0x2000
	global_load_lds_dwordx4 v134, s[10:11]
	s_mov_b32 m0, s29
	s_add_u32 s6, s76, 0x40000
	global_load_lds_dwordx4 v128, s[76:77]
	s_mov_b32 m0, s40
	s_addc_u32 s7, s77, 0
	s_add_i32 s41, s29, 0x4000
	global_load_lds_dwordx4 v132, s[76:77]
	s_mov_b32 m0, s41
	s_add_i32 s59, s29, 0x6000
	v_mov_b32_e32 v131, 0
	global_load_lds_dwordx4 v128, s[6:7]
	s_mov_b32 m0, s59
	v_lshl_add_u64 v[8:9], s[66:67], 0, v[130:131]
	v_mov_b32_e32 v135, v131
	global_load_lds_dwordx4 v132, s[6:7]
	s_mov_b64 s[6:7], 0x80
	v_lshl_add_u64 v[10:11], s[66:67], 0, v[134:135]
	v_mov_b32_e32 v129, v131
	s_add_i32 m0, s29, 0x18000
	v_lshl_add_u64 v[8:9], v[8:9], 0, s[6:7]
	v_lshl_add_u64 v[12:13], s[76:77], 0, v[128:129]
	v_mov_b32_e32 v133, v131
	global_load_lds_dwordx4 v[8:9], off
	v_lshl_add_u64 v[8:9], v[10:11], 0, s[6:7]
	s_add_i32 m0, s29, 0x1a000
	s_add_i32 s60, s29, 0x8000
	v_lshl_add_u64 v[14:15], s[76:77], 0, v[132:133]
	global_load_lds_dwordx4 v[8:9], off
	v_lshl_add_u64 v[8:9], v[12:13], 0, s[6:7]
	s_mov_b32 m0, s60
	s_add_i32 s61, s29, 0xa000
	global_load_lds_dwordx4 v[8:9], off
	v_lshl_add_u64 v[8:9], v[14:15], 0, s[6:7]
	s_mov_b32 m0, s61
	s_add_u32 s10, s66, 0x40080
	global_load_lds_dwordx4 v[8:9], off
	s_addc_u32 s11, s67, 0
	s_add_i32 m0, s29, 0x1c000
	v_readlane_b32 s12, v249, 42
	global_load_lds_dwordx4 v130, s[10:11]
	s_add_i32 m0, s29, 0x1e000
	s_cmp_eq_u32 s12, 1
	global_load_lds_dwordx4 v134, s[10:11]
	s_cselect_b64 s[10:11], -1, 0
	s_cmp_lg_u32 s12, 1
	s_mov_b32 s62, 0
	s_cbranch_scc1 .LBB0_600
	s_barrier

; __device__ __forceinline__ float fexp2(float x) { return __builtin_amdgcn_exp2f(x); }
; __device__ __forceinline__ float frcp(float x) { return __builtin_amdgcn_rcpf(x); }
;     __device__ __forceinline__ void operator()(AccRef acc, const pg8::Unit& u, int wr, int wc, int, int) const {
;     ...
;         float sq[2][4];
; #pragma unroll
;         for (int ai = 0; ai < 2; ++ai)
; #pragma unroll
;             for (int m = 0; m < 4; ++m) sq[ai][m] = ssq[u.pm * 256 + ai * 128 + wr * 64 + m * 16 + fr];
;         asm volatile("" ::: "memory");
; #pragma unroll
;         for (int ai = 0; ai < 2; ++ai)
; #pragma unroll
;             for (int m = 0; m < 4; ++m) {
;                 const int row = u.pm * 256 + ai * 128 + wr * 64 + m * 16 + fr;
;                 const float rstd = __builtin_amdgcn_rsqf(sq[ai][m] * (1.0f / DM) + EPS);
;                 const float rc = -rstd * LOG2E, r2 = rstd * rstd;
;                 unsigned pk[4];
; #pragma unroll
;                 for (int n = 0; n < 2; ++n)
; #pragma unroll
;                     for (int h = 0; h < 2; ++h) {
;                         const f32x2 g2 = {acc[ai][0][m][n][2 * h], acc[ai][0][m][n][2 * h + 1]}, u2 = {acc[ai][1][m][n][2 * h], acc[ai][1][m][n][2 * h + 1]};
;                         const f32x2 x2 = g2 * rc; f32x2 d2; d2.x = fexp2(x2.x); d2.y = fexp2(x2.y); d2 = d2 + 1.0f;
;                         f32x2 q2; q2.x = frcp(d2.x); q2.y = frcp(d2.y);
;                         const f32x2 t2 = (g2 * u2) * r2 * q2;
.LBB0_612:
	s_mov_b64 s[36:37], s[44:45]
	s_mov_b64 s[38:39], s[46:47]
	s_add_u32 s38, s36, 0x22000
	s_addc_u32 s39, s37, 0
	s_lshl_b32 s15, s58, 8
	v_mov_b32_e32 v158, v196
	s_add_i32 s15, s15, s35
	v_pk_mul_f32 v[120:121], v[124:125], v[120:121]
	v_and_or_b32 v156, v158, 15, s15
	v_ashrrev_i32_e32 v157, 31, v156
	v_lshl_add_u64 v[140:141], v[156:157], 2, s[38:39]
	v_mov_b32_e32 v157, v232
	v_or_b32_e32 v154, 16, v156
	v_ashrrev_i32_e32 v155, 31, v154
	v_lshl_add_u64 v[140:141], v[154:155], 2, s[38:39]
	v_mov_b32_e32 v155, v233
	v_or_b32_e32 v152, 32, v156
	v_ashrrev_i32_e32 v153, 31, v152
	v_lshl_add_u64 v[140:141], v[152:153], 2, s[38:39]
	v_mov_b32_e32 v153, v234
	v_or_b32_e32 v150, 48, v156
	v_ashrrev_i32_e32 v151, 31, v150
	v_add_u32_e32 v148, 0x80, v156
	v_lshl_add_u64 v[140:141], v[150:151], 2, s[38:39]
	v_ashrrev_i32_e32 v149, 31, v148
	v_add_u32_e32 v146, 0x90, v156
	v_mov_b32_e32 v151, v235
	v_lshl_add_u64 v[140:141], v[148:149], 2, s[38:39]
	v_ashrrev_i32_e32 v147, 31, v146
	v_add_u32_e32 v144, 0xa0, v156
	v_mov_b32_e32 v149, v236
	v_lshl_add_u64 v[140:141], v[146:147], 2, s[38:39]
	v_ashrrev_i32_e32 v145, 31, v144
	v_mov_b32_e32 v147, v237
	v_lshl_add_u64 v[140:141], v[144:145], 2, s[38:39]
	v_mov_b32_e32 v145, v238
	v_add_u32_e32 v140, 0xb0, v156
	v_ashrrev_i32_e32 v141, 31, v140
	v_lshl_add_u64 v[142:143], v[140:141], 2, s[38:39]
	v_mov_b32_e32 v141, v239
	v_ashrrev_i32_e32 v142, 1, v158
	v_pk_mul_f32 v[122:123], v[126:127], v[122:123]
	v_pk_mul_f32 v[112:113], v[116:117], v[112:113]
	s_lshl_b32 s38, s56, 7
	s_ashr_i32 s39, s38, 31
	s_lshl_b64 s[38:39], s[38:39], 1
	s_add_u32 s15, s36, s38
	s_addc_u32 s31, s37, s39
	s_add_u32 s36, s15, s71
	v_and_b32_e32 v142, -8, v142
	s_addc_u32 s37, s31, 0
	v_ashrrev_i32_e32 v143, 31, v142
	v_pk_mul_f32 v[114:115], v[118:119], v[114:115]
	v_lshl_add_u64 v[142:143], v[142:143], 1, s[36:37]
	s_mov_b64 s[36:37], 0xba00000
	v_lshl_add_u64 v[142:143], v[142:143], 0, s[36:37]
	v_pk_mul_f32 v[104:105], v[108:109], v[104:105]
	v_pk_mul_f32 v[106:107], v[110:111], v[106:107]
	v_pk_mul_f32 v[96:97], v[100:101], v[96:97]
	v_pk_mul_f32 v[98:99], v[102:103], v[98:99]
	v_pk_mul_f32 v[88:89], v[92:93], v[88:89]
	v_pk_mul_f32 v[90:91], v[94:95], v[90:91]
	v_pk_mul_f32 v[80:81], v[84:85], v[80:81]
	v_pk_mul_f32 v[82:83], v[86:87], v[82:83]
	v_pk_mul_f32 v[72:73], v[76:77], v[72:73]
	v_pk_mul_f32 v[74:75], v[78:79], v[74:75]
	v_pk_mul_f32 v[64:65], v[68:69], v[64:65]
	v_pk_mul_f32 v[66:67], v[70:71], v[66:67]
	v_pk_mul_f32 v[56:57], v[60:61], v[56:57]
	v_pk_mul_f32 v[58:59], v[62:63], v[58:59]
	v_pk_mul_f32 v[48:49], v[52:53], v[48:49]
	v_pk_mul_f32 v[50:51], v[54:55], v[50:51]
	v_pk_mul_f32 v[40:41], v[44:45], v[40:41]
	v_pk_mul_f32 v[42:43], v[46:47], v[42:43]
	v_pk_mul_f32 v[32:33], v[36:37], v[32:33]
	v_pk_mul_f32 v[34:35], v[38:39], v[34:35]
	v_pk_mul_f32 v[24:25], v[28:29], v[24:25]
	v_pk_mul_f32 v[26:27], v[30:31], v[26:27]
	v_pk_mul_f32 v[16:17], v[20:21], v[16:17]
	v_pk_mul_f32 v[18:19], v[22:23], v[18:19]
	v_pk_mul_f32 v[8:9], v[12:13], v[8:9]
	v_pk_mul_f32 v[10:11], v[14:15], v[10:11]
	v_pk_mul_f32 v[0:1], v[4:5], v[0:1]
	v_pk_mul_f32 v[2:3], v[6:7], v[2:3]
	s_mov_b64 s[56:57], -1
	s_cmp_lg_u64 s[42:43], 0
	s_cbranch_scc0 .Lp4aq_nopf
	s_add_u32 s84, s44, 0x22000
	s_addc_u32 s85, s45, 0
	s_lshl_b32 s83, s14, 8
	s_add_i32 s83, s83, s35
	v_and_or_b32 v240, v196, 15, s83
	v_lshlrev_b32_e32 v240, 2, v240
	global_load_dword v232, v240, s[84:85]
	global_load_dword v233, v240, s[84:85] offset:64
	global_load_dword v234, v240, s[84:85] offset:128
	global_load_dword v235, v240, s[84:85] offset:192
	global_load_dword v236, v240, s[84:85] offset:512
	global_load_dword v237, v240, s[84:85] offset:576
	global_load_dword v238, v240, s[84:85] offset:640
	global_load_dword v239, v240, s[84:85] offset:704
.Lp4aq_nopf:
	s_andn2_b64 vcc, exec, s[42:43]
	v_fmamk_f32 v157, v157, 0x3a800000, v165
	v_rsq_f32_e32 v157, v157
	s_nop 0
	v_mul_f32_e32 v160, 0xbfb8aa3b, v157
	v_pk_mul_f32 v[166:167], v[124:125], v[160:161] op_sel_hi:[1,0]
	v_pk_mul_f32 v[124:125], v[126:127], v[160:161] op_sel_hi:[1,0]
	v_exp_f32_e32 v166, v166
	v_exp_f32_e32 v167, v167
	v_exp_f32_e32 v124, v124
	v_exp_f32_e32 v125, v125
	v_mul_f32_e32 v158, v157, v157
	v_pk_add_f32 v[166:167], v[166:167], 1.0 op_sel_hi:[1,0]
	v_pk_mul_f32 v[120:121], v[120:121], v[158:159] op_sel_hi:[1,0]
	v_pk_add_f32 v[124:125], v[124:125], 1.0 op_sel_hi:[1,0]
	v_rcp_f32_e32 v166, v166
	v_rcp_f32_e32 v167, v167
	v_rcp_f32_e32 v124, v124
	v_rcp_f32_e32 v125, v125
	v_pk_mul_f32 v[122:123], v[122:123], v[158:159] op_sel_hi:[1,0]
	v_pk_mul_f32 v[120:121], v[120:121], v[166:167]
	v_pk_mul_f32 v[112:113], v[112:113], v[158:159] op_sel_hi:[1,0]
	v_pk_mul_f32 v[122:123], v[122:123], v[124:125]
	v_cvt_pk_bf16_f32 v120, v120, v121
	v_pk_mul_f32 v[114:115], v[114:115], v[158:159] op_sel_hi:[1,0]
	v_cvt_pk_bf16_f32 v121, v122, v123
	v_pk_mul_f32 v[122:123], v[116:117], v[160:161] op_sel_hi:[1,0]
	s_nop 0
	v_exp_f32_e32 v122, v122
	v_exp_f32_e32 v123, v123
	s_nop 0
	v_pk_add_f32 v[122:123], v[122:123], 1.0 op_sel_hi:[1,0]
	s_nop 0
	v_rcp_f32_e32 v122, v122
	v_rcp_f32_e32 v123, v123
	s_nop 0
	v_pk_mul_f32 v[112:113], v[112:113], v[122:123]
	s_nop 0
	v_cvt_pk_bf16_f32 v122, v112, v113
	v_pk_mul_f32 v[112:113], v[118:119], v[160:161] op_sel_hi:[1,0]
	s_nop 0
	v_exp_f32_e32 v112, v112
	v_exp_f32_e32 v113, v113
	s_nop 0
	v_pk_add_f32 v[112:113], v[112:113], 1.0 op_sel_hi:[1,0]
	s_nop 0
	v_rcp_f32_e32 v112, v112
	v_rcp_f32_e32 v113, v113
	s_nop 0
	v_pk_mul_f32 v[112:113], v[114:115], v[112:113]
	s_nop 0
	v_cvt_pk_bf16_f32 v123, v112, v113
	v_mad_i64_i32 v[112:113], s[36:37], v156, s74, v[142:143]
; __device__ __forceinline__ unsigned cvt_pk(float lo, float hi) { unsigned r; asm("v_cvt_pk_bf16_f32 %0, %1, %2" : "=v"(r) : "v"(lo), "v"(hi)); return r; }
; __device__ __forceinline__ float fexp2(float x) { return __builtin_amdgcn_exp2f(x); }
; __device__ __forceinline__ float frcp(float x) { return __builtin_amdgcn_rcpf(x); }
;     __device__ __forceinline__ void operator()(AccRef acc, const pg8::Unit& u, int wr, int wc, int, int) const {
;     ...
;             for (int m = 0; m < 4; ++m) {
;                 const int row = u.pm * 256 + ai * 128 + wr * 64 + m * 16 + fr;
;                 const float rstd = __builtin_amdgcn_rsqf(sq[ai][m] * (1.0f / DM) + EPS);
;                 const float rc = -rstd * LOG2E, r2 = rstd * rstd;
;                 unsigned pk[4];
; #pragma unroll
;                 for (int n = 0; n < 2; ++n)
; #pragma unroll
;                     for (int h = 0; h < 2; ++h) {
;                         const f32x2 g2 = {acc[ai][0][m][n][2 * h], acc[ai][0][m][n][2 * h + 1]}, u2 = {acc[ai][1][m][n][2 * h], acc[ai][1][m][n][2 * h + 1]};
;                         const f32x2 x2 = g2 * rc; f32x2 d2; d2.x = fexp2(x2.x); d2.y = fexp2(x2.y); d2 = d2 + 1.0f;
;                         f32x2 q2; q2.x = frcp(d2.x); q2.y = frcp(d2.y);
;                         const f32x2 t2 = (g2 * u2) * r2 * q2;
;                         pk[2 * n + h] = cvt_pk(t2.x, t2.y);
;                     }
;                 v4u w; w.x = pk[0]; w.y = pk[1]; w.z = pk[2]; w.w = pk[3];
;                 *(v4u*)(ACT + (size_t)row * FF + u.pn * 128 + wc * 32 + 8 * fq) = w;
;             }
	global_store_dwordx4 v[112:113], v[120:123], off
	v_fmamk_f32 v112, v155, 0x3a800000, v165
	v_rsq_f32_e32 v112, v112
	s_nop 0
	v_mul_f32_e32 v114, 0xbfb8aa3b, v112
	v_pk_mul_f32 v[116:117], v[108:109], v[114:115] op_sel_hi:[1,0]
	v_pk_mul_f32 v[108:109], v[110:111], v[114:115] op_sel_hi:[1,0]
	v_exp_f32_e32 v116, v116
	v_exp_f32_e32 v117, v117
	v_exp_f32_e32 v108, v108
	v_exp_f32_e32 v109, v109
	v_mul_f32_e32 v112, v112, v112
	v_pk_add_f32 v[116:117], v[116:117], 1.0 op_sel_hi:[1,0]
	v_pk_mul_f32 v[104:105], v[104:105], v[112:113] op_sel_hi:[1,0]
	v_pk_add_f32 v[108:109], v[108:109], 1.0 op_sel_hi:[1,0]
	v_rcp_f32_e32 v116, v116
	v_rcp_f32_e32 v117, v117
	v_rcp_f32_e32 v108, v108
	v_rcp_f32_e32 v109, v109
	v_pk_mul_f32 v[106:107], v[106:107], v[112:113] op_sel_hi:[1,0]
	v_pk_mul_f32 v[104:105], v[104:105], v[116:117]
	v_pk_mul_f32 v[96:97], v[96:97], v[112:113] op_sel_hi:[1,0]
	v_pk_mul_f32 v[106:107], v[106:107], v[108:109]
	v_cvt_pk_bf16_f32 v104, v104, v105
	v_pk_mul_f32 v[98:99], v[98:99], v[112:113] op_sel_hi:[1,0]
	v_cvt_pk_bf16_f32 v105, v106, v107
	v_pk_mul_f32 v[106:107], v[100:101], v[114:115] op_sel_hi:[1,0]
	s_nop 0
	v_exp_f32_e32 v106, v106
	v_exp_f32_e32 v107, v107
	s_nop 0
	v_pk_add_f32 v[106:107], v[106:107], 1.0 op_sel_hi:[1,0]
	s_nop 0
	v_rcp_f32_e32 v106, v106
	v_rcp_f32_e32 v107, v107
	s_nop 0
	v_pk_mul_f32 v[96:97], v[96:97], v[106:107]
	s_nop 0
	v_cvt_pk_bf16_f32 v106, v96, v97
	v_pk_mul_f32 v[96:97], v[102:103], v[114:115] op_sel_hi:[1,0]
	s_nop 0
	v_exp_f32_e32 v96, v96
	v_exp_f32_e32 v97, v97
	s_nop 0
	v_pk_add_f32 v[96:97], v[96:97], 1.0 op_sel_hi:[1,0]
	s_nop 0
	v_rcp_f32_e32 v96, v96
	v_rcp_f32_e32 v97, v97
	s_nop 0
	v_pk_mul_f32 v[96:97], v[98:99], v[96:97]
	s_nop 0
	v_cvt_pk_bf16_f32 v107, v96, v97
	v_mad_i64_i32 v[96:97], s[36:37], v154, s74, v[142:143]
	global_store_dwordx4 v[96:97], v[104:107], off
	v_fmamk_f32 v96, v153, 0x3a800000, v165
	v_rsq_f32_e32 v97, v96
	s_nop 0
	v_mul_f32_e32 v96, 0xbfb8aa3b, v97
	v_pk_mul_f32 v[100:101], v[92:93], v[96:97] op_sel_hi:[1,0]
	v_pk_mul_f32 v[92:93], v[94:95], v[96:97] op_sel_hi:[1,0]
	v_exp_f32_e32 v100, v100
	v_exp_f32_e32 v101, v101
	v_exp_f32_e32 v92, v92
	v_exp_f32_e32 v93, v93
	v_mul_f32_e32 v98, v97, v97
	v_pk_add_f32 v[100:101], v[100:101], 1.0 op_sel_hi:[1,0]
	v_pk_mul_f32 v[88:89], v[88:89], v[98:99] op_sel_hi:[1,0]
	v_pk_add_f32 v[92:93], v[92:93], 1.0 op_sel_hi:[1,0]
	v_rcp_f32_e32 v100, v100
	v_rcp_f32_e32 v101, v101
	v_rcp_f32_e32 v92, v92
	v_rcp_f32_e32 v93, v93
	v_pk_mul_f32 v[90:91], v[90:91], v[98:99] op_sel_hi:[1,0]
	v_pk_mul_f32 v[88:89], v[88:89], v[100:101]
	v_pk_mul_f32 v[80:81], v[80:81], v[98:99] op_sel_hi:[1,0]
	v_pk_mul_f32 v[90:91], v[90:91], v[92:93]
	v_cvt_pk_bf16_f32 v88, v88, v89
	v_pk_mul_f32 v[82:83], v[82:83], v[98:99] op_sel_hi:[1,0]
	v_cvt_pk_bf16_f32 v89, v90, v91
	v_pk_mul_f32 v[90:91], v[84:85], v[96:97] op_sel_hi:[1,0]
	s_nop 0
	v_exp_f32_e32 v90, v90
	v_exp_f32_e32 v91, v91
	s_nop 0
	v_pk_add_f32 v[90:91], v[90:91], 1.0 op_sel_hi:[1,0]
	s_nop 0
	v_rcp_f32_e32 v90, v90
	v_rcp_f32_e32 v91, v91
	s_nop 0
	v_pk_mul_f32 v[80:81], v[80:81], v[90:91]
	s_nop 0
	v_cvt_pk_bf16_f32 v90, v80, v81
	v_pk_mul_f32 v[80:81], v[86:87], v[96:97] op_sel_hi:[1,0]
	s_nop 0
	v_exp_f32_e32 v80, v80
	v_exp_f32_e32 v81, v81
	s_nop 0
	v_pk_add_f32 v[80:81], v[80:81], 1.0 op_sel_hi:[1,0]
	s_nop 0
	v_rcp_f32_e32 v80, v80
	v_rcp_f32_e32 v81, v81
	s_nop 0
	v_pk_mul_f32 v[80:81], v[82:83], v[80:81]
	s_nop 0
	v_cvt_pk_bf16_f32 v91, v80, v81
	v_mad_i64_i32 v[80:81], s[36:37], v152, s74, v[142:143]
	global_store_dwordx4 v[80:81], v[88:91], off
	v_fmamk_f32 v80, v151, 0x3a800000, v165
	v_rsq_f32_e32 v81, v80
	s_nop 0
	v_mul_f32_e32 v80, 0xbfb8aa3b, v81
	v_pk_mul_f32 v[84:85], v[76:77], v[80:81] op_sel_hi:[1,0]
	v_pk_mul_f32 v[76:77], v[78:79], v[80:81] op_sel_hi:[1,0]
	v_exp_f32_e32 v84, v84
	v_exp_f32_e32 v85, v85
	v_exp_f32_e32 v76, v76
	v_exp_f32_e32 v77, v77
	v_mul_f32_e32 v82, v81, v81
	v_pk_add_f32 v[84:85], v[84:85], 1.0 op_sel_hi:[1,0]
	v_pk_mul_f32 v[72:73], v[72:73], v[82:83] op_sel_hi:[1,0]
	v_pk_add_f32 v[76:77], v[76:77], 1.0 op_sel_hi:[1,0]
	v_rcp_f32_e32 v84, v84
	v_rcp_f32_e32 v85, v85
	v_rcp_f32_e32 v76, v76
	v_rcp_f32_e32 v77, v77
	v_pk_mul_f32 v[74:75], v[74:75], v[82:83] op_sel_hi:[1,0]
	v_pk_mul_f32 v[72:73], v[72:73], v[84:85]
	v_pk_mul_f32 v[64:65], v[64:65], v[82:83] op_sel_hi:[1,0]
	v_pk_mul_f32 v[74:75], v[74:75], v[76:77]
	v_cvt_pk_bf16_f32 v72, v72, v73
	v_pk_mul_f32 v[66:67], v[66:67], v[82:83] op_sel_hi:[1,0]
	v_cvt_pk_bf16_f32 v73, v74, v75
	v_pk_mul_f32 v[74:75], v[68:69], v[80:81] op_sel_hi:[1,0]
	s_nop 0
	v_exp_f32_e32 v74, v74
	v_exp_f32_e32 v75, v75
	s_nop 0
	v_pk_add_f32 v[74:75], v[74:75], 1.0 op_sel_hi:[1,0]
	s_nop 0
	v_rcp_f32_e32 v74, v74
	v_rcp_f32_e32 v75, v75
	s_nop 0
	v_pk_mul_f32 v[64:65], v[64:65], v[74:75]
	s_nop 0
	v_cvt_pk_bf16_f32 v74, v64, v65
	v_pk_mul_f32 v[64:65], v[70:71], v[80:81] op_sel_hi:[1,0]
	s_nop 0
	v_exp_f32_e32 v64, v64
	v_exp_f32_e32 v65, v65
	s_nop 0
	v_pk_add_f32 v[64:65], v[64:65], 1.0 op_sel_hi:[1,0]
	s_nop 0
	v_rcp_f32_e32 v64, v64
	v_rcp_f32_e32 v65, v65
	s_nop 0
	v_pk_mul_f32 v[64:65], v[66:67], v[64:65]
	s_nop 0
	v_cvt_pk_bf16_f32 v75, v64, v65
	v_mad_i64_i32 v[64:65], s[36:37], v150, s74, v[142:143]
	global_store_dwordx4 v[64:65], v[72:75], off
	v_fmamk_f32 v64, v149, 0x3a800000, v165
	v_rsq_f32_e32 v65, v64
	s_nop 0
	v_mul_f32_e32 v64, 0xbfb8aa3b, v65
	v_pk_mul_f32 v[68:69], v[60:61], v[64:65] op_sel_hi:[1,0]
	v_pk_mul_f32 v[60:61], v[62:63], v[64:65] op_sel_hi:[1,0]
	v_exp_f32_e32 v68, v68
	v_exp_f32_e32 v69, v69
	v_exp_f32_e32 v60, v60
	v_exp_f32_e32 v61, v61
	v_mul_f32_e32 v66, v65, v65
; __device__ __forceinline__ unsigned cvt_pk(float lo, float hi) { unsigned r; asm("v_cvt_pk_bf16_f32 %0, %1, %2" : "=v"(r) : "v"(lo), "v"(hi)); return r; }
; __device__ __forceinline__ float fexp2(float x) { return __builtin_amdgcn_exp2f(x); }
; __device__ __forceinline__ float frcp(float x) { return __builtin_amdgcn_rcpf(x); }
;     __device__ __forceinline__ void operator()(AccRef acc, const pg8::Unit& u, int wr, int wc, int, int) const {
;     ...
;             for (int m = 0; m < 4; ++m) {
;                 const int row = u.pm * 256 + ai * 128 + wr * 64 + m * 16 + fr;
;                 const float rstd = __builtin_amdgcn_rsqf(sq[ai][m] * (1.0f / DM) + EPS);
;                 const float rc = -rstd * LOG2E, r2 = rstd * rstd;
;                 unsigned pk[4];
; #pragma unroll
;                 for (int n = 0; n < 2; ++n)
; #pragma unroll
;                     for (int h = 0; h < 2; ++h) {
;                         const f32x2 g2 = {acc[ai][0][m][n][2 * h], acc[ai][0][m][n][2 * h + 1]}, u2 = {acc[ai][1][m][n][2 * h], acc[ai][1][m][n][2 * h + 1]};
;                         const f32x2 x2 = g2 * rc; f32x2 d2; d2.x = fexp2(x2.x); d2.y = fexp2(x2.y); d2 = d2 + 1.0f;
;                         f32x2 q2; q2.x = frcp(d2.x); q2.y = frcp(d2.y);
;                         const f32x2 t2 = (g2 * u2) * r2 * q2;
;                         pk[2 * n + h] = cvt_pk(t2.x, t2.y);
;                     }
;                 v4u w; w.x = pk[0]; w.y = pk[1]; w.z = pk[2]; w.w = pk[3];
;                 *(v4u*)(ACT + (size_t)row * FF + u.pn * 128 + wc * 32 + 8 * fq) = w;
;             }
	v_pk_add_f32 v[68:69], v[68:69], 1.0 op_sel_hi:[1,0]
	v_pk_mul_f32 v[56:57], v[56:57], v[66:67] op_sel_hi:[1,0]
	v_pk_add_f32 v[60:61], v[60:61], 1.0 op_sel_hi:[1,0]
	v_rcp_f32_e32 v68, v68
	v_rcp_f32_e32 v69, v69
	v_rcp_f32_e32 v60, v60
	v_rcp_f32_e32 v61, v61
	v_pk_mul_f32 v[58:59], v[58:59], v[66:67] op_sel_hi:[1,0]
	v_pk_mul_f32 v[56:57], v[56:57], v[68:69]
	v_pk_mul_f32 v[48:49], v[48:49], v[66:67] op_sel_hi:[1,0]
	v_pk_mul_f32 v[58:59], v[58:59], v[60:61]
	v_cvt_pk_bf16_f32 v56, v56, v57
	v_pk_mul_f32 v[50:51], v[50:51], v[66:67] op_sel_hi:[1,0]
	v_cvt_pk_bf16_f32 v57, v58, v59
	v_pk_mul_f32 v[58:59], v[52:53], v[64:65] op_sel_hi:[1,0]
	s_nop 0
	v_exp_f32_e32 v58, v58
	v_exp_f32_e32 v59, v59
	s_nop 0
	v_pk_add_f32 v[58:59], v[58:59], 1.0 op_sel_hi:[1,0]
	s_nop 0
	v_rcp_f32_e32 v58, v58
	v_rcp_f32_e32 v59, v59
	s_nop 0
	v_pk_mul_f32 v[48:49], v[48:49], v[58:59]
	s_nop 0
	v_cvt_pk_bf16_f32 v58, v48, v49
	v_pk_mul_f32 v[48:49], v[54:55], v[64:65] op_sel_hi:[1,0]
	s_nop 0
	v_exp_f32_e32 v48, v48
	v_exp_f32_e32 v49, v49
	s_nop 0
	v_pk_add_f32 v[48:49], v[48:49], 1.0 op_sel_hi:[1,0]
	s_nop 0
	v_rcp_f32_e32 v48, v48
	v_rcp_f32_e32 v49, v49
	s_nop 0
	v_pk_mul_f32 v[48:49], v[50:51], v[48:49]
	s_nop 0
	v_cvt_pk_bf16_f32 v59, v48, v49
	v_mad_i64_i32 v[48:49], s[36:37], v148, s74, v[142:143]
	global_store_dwordx4 v[48:49], v[56:59], off
	v_fmamk_f32 v48, v147, 0x3a800000, v165
	v_rsq_f32_e32 v49, v48
	s_nop 0
	v_mul_f32_e32 v48, 0xbfb8aa3b, v49
	v_pk_mul_f32 v[52:53], v[44:45], v[48:49] op_sel_hi:[1,0]
	v_pk_mul_f32 v[44:45], v[46:47], v[48:49] op_sel_hi:[1,0]
	v_exp_f32_e32 v52, v52
	v_exp_f32_e32 v53, v53
	v_exp_f32_e32 v44, v44
	v_exp_f32_e32 v45, v45
	v_mul_f32_e32 v50, v49, v49
	v_pk_add_f32 v[52:53], v[52:53], 1.0 op_sel_hi:[1,0]
	v_pk_mul_f32 v[40:41], v[40:41], v[50:51] op_sel_hi:[1,0]
	v_pk_add_f32 v[44:45], v[44:45], 1.0 op_sel_hi:[1,0]
	v_rcp_f32_e32 v52, v52
	v_rcp_f32_e32 v53, v53
	v_rcp_f32_e32 v44, v44
	v_rcp_f32_e32 v45, v45
	v_pk_mul_f32 v[42:43], v[42:43], v[50:51] op_sel_hi:[1,0]
	v_pk_mul_f32 v[40:41], v[40:41], v[52:53]
	v_pk_mul_f32 v[32:33], v[32:33], v[50:51] op_sel_hi:[1,0]
	v_pk_mul_f32 v[42:43], v[42:43], v[44:45]
	v_cvt_pk_bf16_f32 v40, v40, v41
	v_pk_mul_f32 v[34:35], v[34:35], v[50:51] op_sel_hi:[1,0]
	v_cvt_pk_bf16_f32 v41, v42, v43
	v_pk_mul_f32 v[42:43], v[36:37], v[48:49] op_sel_hi:[1,0]
	s_nop 0
	v_exp_f32_e32 v42, v42
	v_exp_f32_e32 v43, v43
	s_nop 0
	v_pk_add_f32 v[42:43], v[42:43], 1.0 op_sel_hi:[1,0]
	s_nop 0
	v_rcp_f32_e32 v42, v42
	v_rcp_f32_e32 v43, v43
	s_nop 0
	v_pk_mul_f32 v[32:33], v[32:33], v[42:43]
	s_nop 0
	v_cvt_pk_bf16_f32 v42, v32, v33
	v_pk_mul_f32 v[32:33], v[38:39], v[48:49] op_sel_hi:[1,0]
	s_nop 0
	v_exp_f32_e32 v32, v32
	v_exp_f32_e32 v33, v33
	s_nop 0
	v_pk_add_f32 v[32:33], v[32:33], 1.0 op_sel_hi:[1,0]
	s_nop 0
	v_rcp_f32_e32 v32, v32
	v_rcp_f32_e32 v33, v33
	s_nop 0
	v_pk_mul_f32 v[32:33], v[34:35], v[32:33]
	s_nop 0
	v_cvt_pk_bf16_f32 v43, v32, v33
	v_mad_i64_i32 v[32:33], s[36:37], v146, s74, v[142:143]
	global_store_dwordx4 v[32:33], v[40:43], off
	v_fmamk_f32 v32, v145, 0x3a800000, v165
	v_rsq_f32_e32 v33, v32
	s_nop 0
	v_mul_f32_e32 v32, 0xbfb8aa3b, v33
	v_pk_mul_f32 v[36:37], v[28:29], v[32:33] op_sel_hi:[1,0]
	v_pk_mul_f32 v[28:29], v[30:31], v[32:33] op_sel_hi:[1,0]
	v_exp_f32_e32 v36, v36
	v_exp_f32_e32 v37, v37
	v_exp_f32_e32 v28, v28
	v_exp_f32_e32 v29, v29
	v_mul_f32_e32 v34, v33, v33
	v_pk_add_f32 v[36:37], v[36:37], 1.0 op_sel_hi:[1,0]
	v_pk_mul_f32 v[24:25], v[24:25], v[34:35] op_sel_hi:[1,0]
	v_pk_add_f32 v[28:29], v[28:29], 1.0 op_sel_hi:[1,0]
	v_rcp_f32_e32 v36, v36
	v_rcp_f32_e32 v37, v37
	v_rcp_f32_e32 v28, v28
	v_rcp_f32_e32 v29, v29
	v_pk_mul_f32 v[26:27], v[26:27], v[34:35] op_sel_hi:[1,0]
	v_pk_mul_f32 v[24:25], v[24:25], v[36:37]
	v_pk_mul_f32 v[16:17], v[16:17], v[34:35] op_sel_hi:[1,0]
	v_pk_mul_f32 v[26:27], v[26:27], v[28:29]
	v_cvt_pk_bf16_f32 v24, v24, v25
	v_pk_mul_f32 v[18:19], v[18:19], v[34:35] op_sel_hi:[1,0]
	v_cvt_pk_bf16_f32 v25, v26, v27
	v_pk_mul_f32 v[26:27], v[20:21], v[32:33] op_sel_hi:[1,0]
	s_nop 0
	v_exp_f32_e32 v26, v26
	v_exp_f32_e32 v27, v27
	s_nop 0
	v_pk_add_f32 v[26:27], v[26:27], 1.0 op_sel_hi:[1,0]
	s_nop 0
	v_rcp_f32_e32 v26, v26
	v_rcp_f32_e32 v27, v27
	s_nop 0
	v_pk_mul_f32 v[16:17], v[16:17], v[26:27]
	s_nop 0
	v_cvt_pk_bf16_f32 v26, v16, v17
	v_pk_mul_f32 v[16:17], v[22:23], v[32:33] op_sel_hi:[1,0]
	s_nop 0
	v_exp_f32_e32 v16, v16
	v_exp_f32_e32 v17, v17
	s_nop 0
	v_pk_add_f32 v[16:17], v[16:17], 1.0 op_sel_hi:[1,0]
	s_nop 0
	v_rcp_f32_e32 v16, v16
	v_rcp_f32_e32 v17, v17
	s_nop 0
	v_pk_mul_f32 v[16:17], v[18:19], v[16:17]
	s_nop 0
	v_cvt_pk_bf16_f32 v27, v16, v17
	v_mad_i64_i32 v[16:17], s[36:37], v144, s74, v[142:143]
	global_store_dwordx4 v[16:17], v[24:27], off
	v_fmamk_f32 v16, v141, 0x3a800000, v165
	v_rsq_f32_e32 v17, v16
	s_nop 0
	v_mul_f32_e32 v16, 0xbfb8aa3b, v17
	v_pk_mul_f32 v[20:21], v[12:13], v[16:17] op_sel_hi:[1,0]
	v_pk_mul_f32 v[12:13], v[14:15], v[16:17] op_sel_hi:[1,0]
	v_exp_f32_e32 v20, v20
	v_exp_f32_e32 v21, v21
	v_exp_f32_e32 v12, v12
	v_exp_f32_e32 v13, v13
	v_mul_f32_e32 v18, v17, v17
	v_pk_add_f32 v[20:21], v[20:21], 1.0 op_sel_hi:[1,0]
	v_pk_mul_f32 v[8:9], v[8:9], v[18:19] op_sel_hi:[1,0]
	v_pk_add_f32 v[12:13], v[12:13], 1.0 op_sel_hi:[1,0]
	v_rcp_f32_e32 v20, v20
	v_rcp_f32_e32 v21, v21
	v_rcp_f32_e32 v12, v12
	v_rcp_f32_e32 v13, v13
	v_pk_mul_f32 v[10:11], v[10:11], v[18:19] op_sel_hi:[1,0]
	v_pk_mul_f32 v[8:9], v[8:9], v[20:21]
	v_pk_mul_f32 v[0:1], v[0:1], v[18:19] op_sel_hi:[1,0]
	v_pk_mul_f32 v[10:11], v[10:11], v[12:13]
	v_cvt_pk_bf16_f32 v8, v8, v9
	v_pk_mul_f32 v[2:3], v[2:3], v[18:19] op_sel_hi:[1,0]
	v_cvt_pk_bf16_f32 v9, v10, v11
	v_pk_mul_f32 v[10:11], v[4:5], v[16:17] op_sel_hi:[1,0]
	s_nop 0
	v_exp_f32_e32 v10, v10
	v_exp_f32_e32 v11, v11
	s_nop 0
	v_pk_add_f32 v[10:11], v[10:11], 1.0 op_sel_hi:[1,0]
	s_nop 0
	v_rcp_f32_e32 v10, v10
	v_rcp_f32_e32 v11, v11
	s_nop 0
	v_pk_mul_f32 v[0:1], v[0:1], v[10:11]
	s_nop 0
	v_cvt_pk_bf16_f32 v10, v0, v1
	v_pk_mul_f32 v[0:1], v[6:7], v[16:17] op_sel_hi:[1,0]
	s_nop 0
	v_exp_f32_e32 v0, v0
	v_exp_f32_e32 v1, v1
	s_nop 0
	v_pk_add_f32 v[0:1], v[0:1], 1.0 op_sel_hi:[1,0]
	s_nop 0
	v_rcp_f32_e32 v0, v0
	v_rcp_f32_e32 v1, v1
	s_nop 0
	v_pk_mul_f32 v[0:1], v[2:3], v[0:1]
	s_nop 0
	v_cvt_pk_bf16_f32 v11, v0, v1
	v_mad_i64_i32 v[0:1], s[36:37], v140, s74, v[142:143]
	global_store_dwordx4 v[0:1], v[8:11], off
	s_cbranch_vccnz .LBB0_602
	s_andn2_b64 vcc, exec, s[10:11]
	s_cbranch_vccnz .LBB0_601
	s_barrier
	s_branch .LBB0_601

; __device__ __forceinline__ int lane_id() { int l = __builtin_amdgcn_mbcnt_hi(~0u, __builtin_amdgcn_mbcnt_lo(~0u, 0u)); asm volatile("" : "+v"(l)); return l; }
; #define PG8_BAR __builtin_amdgcn_s_barrier()
; template <int KK, class Epi, class Sched, bool ALIGN_EPI = true>
; __device__ __forceinline__ void gemm_phase(LAS unsigned char* lds, const bf16* gA, const bf16* gBt, const Sched& S, const Epi& E, const int wid) {
;     const int lane = lane_id();
;     const int tid = wid * 64 + lane, wr = wid >> 2, wc = wid & 3, fr = lane & 15, fq = lane >> 4;
;     constexpr int K = KK, nt = K / BK;
;     unsigned voffA[2], voffB[2];
; #pragma unroll
;     for (int i = 0; i < 2; ++i) { int R, C; stage_rc(tid * 16 + i * 8192, R, C); const int Rb = Epi::PERM ? ((R & ~31) + perm32(R & 31)) : R;
;         voffA[i] = (unsigned)(R * K + C) * 2u; voffB[i] = (unsigned)(Rb * K + C) * 2u; }
;     const size_t kstep = (size_t)(BK * 2);
;     const size_t hstep = (size_t)HALF * K * 2;
;     const size_t tstep = 2 * hstep;
;     const unsigned ldsw = (unsigned)wid * 1024u;
;     const int aoff = lds_byte(wr * 64 + fr, fq * 8), boff = lds_byte(wc * 32 + fr, fq * 8);
;     ...
;     Unit cur, nxt; int ui = 0;
;     if (!S.next(0, cur)) return;
;     f32x4 acc[2][2][4][2];
; #pragma unroll
;     for (int a = 0; a < 2; ++a)
; #pragma unroll
;         for (int b = 0; b < 2; ++b)
; #pragma unroll
;             for (int m = 0; m < 4; ++m)
; #pragma unroll
;                 for (int n = 0; n < 2; ++n) acc[a][b][m][n] = (f32x4){0.f, 0.f, 0.f, 0.f};
;     bf16x8 At[4][2], B0[2][2], B1[2][2];
;     const char* cA = (const char*)gA + (size_t)cur.pm * tstep; const char* cB = (const char*)gBt + (size_t)cur.pn * tstep;
;     PG8_STAGE(PG8_SB(0, 0), cB, voffB); PG8_STAGE(PG8_SB(0, 1), cB + hstep, voffB); PG8_STAGE(PG8_SA(0, 0), cA, voffA); PG8_STAGE(PG8_SA(0, 1), cA + hstep, voffA);
;     PG8_STAGE(PG8_SB(1, 0), cB + kstep, voffB); PG8_STAGE(PG8_SA(1, 0), cA + kstep, voffA); PG8_STAGE(PG8_SB(1, 1), cB + hstep + kstep, voffB);
;     if (wr == 1) PG8_BAR;
;     __device__ __forceinline__ void operator()(AccRef acc, const pg8::Unit& u, int wr, int wc, int, int) const {
;     ...
;             for (int m = 0; m < 4; ++m) sq[ai][m] = ssq[pm * 256 + ai * 128 + wr * 64 + m * 16 + fr];
.LBB0_891:
	s_andn2_b64 vcc, exec, s[6:7]
	s_cbranch_vccnz .LBB0_1038
	s_add_u32 s78, s20, 0x43000
	s_addc_u32 s79, s21, 0
	s_lshl_b32 s80, s66, 8
	s_add_i32 s80, s80, s35
	v_and_or_b32 v240, v196, 15, s80
	v_lshlrev_b32_e32 v240, 2, v240
	global_load_dword v232, v240, s[78:79]
	global_load_dword v233, v240, s[78:79] offset:64
	global_load_dword v234, v240, s[78:79] offset:128
	global_load_dword v235, v240, s[78:79] offset:192
	global_load_dword v236, v240, s[78:79] offset:512
	global_load_dword v237, v240, s[78:79] offset:576
	global_load_dword v238, v240, s[78:79] offset:640
	global_load_dword v239, v240, s[78:79] offset:704
	v_lshlrev_b32_e32 v4, 4, v0
	v_add_u32_e32 v5, s33, v4
	v_ashrrev_i32_e32 v1, 31, v5
	v_lshrrev_b32_e32 v1, 22, v1
	v_add_u32_e32 v1, v5, v1
	v_ashrrev_i32_e32 v1, 10, v1
	v_mul_i32_i24_e32 v2, 0x400, v1
	v_sub_u32_e32 v2, v5, v2
	v_lshrrev_b32_e32 v3, 4, v2
	v_bitop3_b32 v3, v3, v2, 32 bitop3:0x6c
	v_lshlrev_b32_e32 v2, 3, v1
	v_and_b32_e32 v6, -16, v2
	v_ashrrev_i32_e32 v2, 31, v3
	v_lshrrev_b32_e32 v2, 26, v2
	v_add_u32_e32 v7, v3, v2
	v_ashrrev_i32_e32 v2, 6, v7
	v_and_b32_e32 v7, 0xc0, v7
	v_sub_u32_e32 v3, v3, v7
	v_mov_b32_e32 v7, 1
	v_lshlrev_b32_e32 v8, 5, v1
	v_ashrrev_i16_sdwa v3, v7, sext(v3) dst_sel:DWORD dst_unused:UNUSED_PAD src0_sel:DWORD src1_sel:BYTE_0
	v_and_b32_e32 v8, 32, v8
	v_bfe_i32 v3, v3, 0, 16
	v_add_u32_e32 v6, v2, v6
	v_and_b32_e32 v11, 3, v2
	s_mov_b32 s0, 0x1fffe0
	v_add_lshl_u32 v8, v8, v3, 1
	v_lshlrev_b32_e32 v9, 1, v6
	v_lshrrev_b32_e32 v10, 2, v6
	v_and_or_b32 v11, v6, s0, v11
	v_lshl_add_u32 v128, v6, 11, v8
	v_add_u32_e32 v6, 0x2000, v5
	v_ashrrev_i32_e32 v5, 31, v6
	v_lshrrev_b32_e32 v5, 22, v5
	v_and_b32_e32 v9, 24, v9
	v_and_b32_e32 v10, 4, v10
	v_add_u32_e32 v5, v6, v5
	v_or3_b32 v9, v11, v10, v9
	v_ashrrev_i32_e32 v5, 10, v5
	v_lshl_add_u32 v130, v9, 11, v8
	v_mul_i32_i24_e32 v8, 0x400, v5
	v_sub_u32_e32 v6, v6, v8
	v_lshrrev_b32_e32 v8, 4, v6
	v_bitop3_b32 v8, v8, v6, 32 bitop3:0x6c
	v_lshlrev_b32_e32 v6, 3, v5
	v_and_b32_e32 v9, -16, v6
	v_ashrrev_i32_e32 v6, 31, v8
	v_lshrrev_b32_e32 v6, 26, v6
	v_add_u32_e32 v10, v8, v6
	s_add_u32 s65, s20, 0x1b80000
	v_ashrrev_i32_e32 v6, 6, v10
	v_and_b32_e32 v10, 0xffc0, v10
	s_addc_u32 s69, s21, 0
	v_sub_u32_e32 v8, v8, v10
	s_add_u32 s86, s20, 0x3600000
	v_add_u32_e32 v9, v6, v9
	v_lshrrev_b16_e32 v10, 7, v8
	v_and_b32_e32 v12, 3, v6
	s_addc_u32 s87, s21, 0
	s_ashr_i32 s67, s66, 31
	s_ashr_i32 s15, s14, 31
	v_and_b32_e32 v10, 1, v10
	v_and_or_b32 v12, v9, s0, v12
	s_lshl_b64 s[0:1], s[66:67], 19
	s_lshl_b64 s[2:3], s[14:15], 19
	v_add_u16_e32 v8, v8, v10
	s_add_u32 s6, s65, s2
	v_lshlrev_b32_e32 v11, 5, v5
	v_ashrrev_i16_sdwa v7, v7, sext(v8) dst_sel:DWORD dst_unused:UNUSED_PAD src0_sel:DWORD src1_sel:BYTE_0
	v_lshlrev_b32_e32 v8, 1, v9
	v_lshrrev_b32_e32 v10, 2, v9
	s_addc_u32 s7, s69, s3
	s_add_i32 s67, s33, 0
	v_and_b32_e32 v11, 32, v11
	v_bfe_i32 v7, v7, 0, 16
	v_and_b32_e32 v8, 24, v8
	v_and_b32_e32 v10, 4, v10
	s_add_i32 m0, s67, 0x10000
	v_or3_b32 v8, v12, v10, v8
	v_add_lshl_u32 v10, v11, v7, 1
	global_load_lds_dwordx4 v130, s[6:7]
	s_add_i32 m0, s67, 0x12000
	v_lshl_add_u32 v134, v8, 11, v10
	s_add_u32 s2, s6, 0x40000
	global_load_lds_dwordx4 v134, s[6:7]
	s_addc_u32 s3, s7, 0
	s_add_i32 m0, s67, 0x14000
	v_lshl_add_u32 v132, v9, 11, v10
	global_load_lds_dwordx4 v130, s[2:3]
	s_add_i32 m0, s67, 0x16000
	s_add_u32 s8, s86, s0
	s_addc_u32 s9, s87, s1
	s_add_i32 s88, s67, 0x2000
	global_load_lds_dwordx4 v134, s[2:3]
	s_mov_b32 m0, s67
	s_add_u32 s0, s8, 0x40000
	v_mov_b32_e32 v137, 0
	global_load_lds_dwordx4 v128, s[8:9]
	s_mov_b32 m0, s88
	s_addc_u32 s1, s9, 0
	s_add_i32 s89, s67, 0x4000
	v_mov_b32_e32 v131, v137
	global_load_lds_dwordx4 v132, s[8:9]
	s_mov_b32 m0, s89
	s_add_i32 s74, s67, 0x6000
	v_lshl_add_u64 v[8:9], s[6:7], 0, v[130:131]
	v_mov_b32_e32 v135, v137
	global_load_lds_dwordx4 v128, s[0:1]
	s_mov_b32 m0, s74
	s_mov_b64 s[24:25], 0x80
	v_lshl_add_u64 v[10:11], s[6:7], 0, v[134:135]
	v_mov_b32_e32 v129, v137
	global_load_lds_dwordx4 v132, s[0:1]
	s_add_i32 m0, s67, 0x18000
	v_lshl_add_u64 v[8:9], v[8:9], 0, s[24:25]
	v_lshl_add_u64 v[12:13], s[8:9], 0, v[128:129]
	v_mov_b32_e32 v133, v137
	global_load_lds_dwordx4 v[8:9], off
	v_lshl_add_u64 v[8:9], v[10:11], 0, s[24:25]
	s_add_i32 m0, s67, 0x1a000
	s_add_i32 s75, s67, 0x8000
	v_lshl_add_u64 v[14:15], s[8:9], 0, v[132:133]
	global_load_lds_dwordx4 v[8:9], off
	v_lshl_add_u64 v[8:9], v[12:13], 0, s[24:25]
	s_mov_b32 m0, s75
	s_add_i32 s18, s67, 0xa000
	global_load_lds_dwordx4 v[8:9], off
	v_lshl_add_u64 v[8:9], v[14:15], 0, s[24:25]
	s_mov_b32 m0, s18
	s_add_u32 s0, s6, 0x40080
	global_load_lds_dwordx4 v[8:9], off
	s_addc_u32 s1, s7, 0
	s_add_i32 m0, s67, 0x1c000
	s_mov_b32 s37, 0
	global_load_lds_dwordx4 v130, s[0:1]
	s_add_i32 m0, s67, 0x1e000
	s_nop 0
	global_load_lds_dwordx4 v134, s[0:1]
	v_readlane_b32 s0, v249, 42
	s_cmp_eq_u32 s0, 1
	s_cselect_b64 s[26:27], -1, 0
	s_cmp_lg_u32 s0, 1
	s_cbranch_scc1 .LBB0_894
	s_barrier

;     __device__ __forceinline__ void operator()(AccRef acc, const pg8::Unit& u, int wr, int wc, int, int) const {
;     ...
;         float sq[2][4];
; #pragma unroll
;         for (int ai = 0; ai < 2; ++ai)
; #pragma unroll
;             for (int m = 0; m < 4; ++m) sq[ai][m] = ssq[pm * 256 + ai * 128 + wr * 64 + m * 16 + fr];
;         asm volatile("" ::: "memory");
; #pragma unroll
;         for (int ai = 0; ai < 2; ++ai)
; #pragma unroll
;             for (int m = 0; m < 4; ++m) {
;                 const int row = pm * 256 + ai * 128 + wr * 64 + m * 16 + fr;
;                 const float rstd = __builtin_amdgcn_rsqf(sq[ai][m] * (1.0f / DM) + EPS) * (isq ? QSCALE : 1.0f);
;                 const int pos = samp ? 2048 + ((row - MP) & 63) : (row & 16383);
; #pragma unroll
;                 for (int bj = 0; bj < 2; ++bj) {
;                     const int c0 = pn * 256 + bj * 128 + wc * 32 + 8 * fq;
;                     float v[8];
; #pragma unroll
;                     for (int j = 0; j < 4; ++j) { v[j] = acc[ai][bj][m][0][j] * rstd; v[4 + j] = acc[ai][bj][m][1][j] * rstd; }
;                     const bool ropet = (pn == 6 || pn == 7 || (pn == 8 && bj == 0)) && ((wc & 1) == 0);
;                     if (ropet) {
;                         float pv[8];
; #pragma unroll
;                         for (int j = 0; j < 8; ++j) pv[j] = __shfl_xor(v[j], 16);
;                         if (fq < 2) {
;                             const f32x4* cs = (const f32x4*)(rope + (size_t)pos * 16);
;                             const float sg = (fq == 0) ? -1.f : 1.f;
; #pragma unroll
;                             for (int jj = 0; jj < 4; ++jj) { const f32x4 t = cs[jj];
;                                 v[2 * jj] = v[2 * jj] * t[0] + sg * pv[2 * jj] * t[1];
;                                 v[2 * jj + 1] = v[2 * jj + 1] * t[2] + sg * pv[2 * jj + 1] * t[3]; }
;                         }
.LBB0_906:
	s_mov_b64 s[10:11], s[20:21]
	s_mov_b64 s[58:59], s[22:23]
	s_add_u32 s8, s10, 0x43000
	s_addc_u32 s9, s11, 0
	s_cmpk_gt_i32 s66, 0x7f
	s_cselect_b64 s[6:7], -1, 0
	s_cmp_lt_i32 s14, 2
	s_cselect_b64 s[2:3], -1, 0
	s_and_b32 s12, s14, -2
	s_cmp_eq_u32 s12, 6
	s_cselect_b64 s[84:85], -1, 0
	v_mov_b32_e32 v136, v196
	s_or_b64 vcc, s[2:3], s[84:85]
	s_lshl_b32 s2, s66, 8
	s_add_i32 s2, s2, s35
	v_and_b32_e32 v173, 15, v136
	v_or_b32_e32 v144, s2, v173
	v_ashrrev_i32_e32 v145, 31, v144
	v_or_b32_e32 v154, 16, v144
	v_lshl_add_u64 v[146:147], v[144:145], 2, s[8:9]
	v_ashrrev_i32_e32 v155, 31, v154
	v_or_b32_e32 v152, 32, v144
	v_mov_b32_e32 v148, v232
	v_lshl_add_u64 v[146:147], v[154:155], 2, s[8:9]
	v_ashrrev_i32_e32 v153, 31, v152
	v_or_b32_e32 v150, 48, v144
	v_mov_b32_e32 v178, v233
	v_lshl_add_u64 v[146:147], v[152:153], 2, s[8:9]
	v_ashrrev_i32_e32 v151, 31, v150
	v_mov_b32_e32 v177, v234
	v_lshl_add_u64 v[146:147], v[150:151], 2, s[8:9]
	v_mov_b32_e32 v176, v235
	v_add_u32_e32 v146, 0x80, v144
	v_ashrrev_i32_e32 v147, 31, v146
	v_lshl_add_u64 v[146:147], v[146:147], 2, s[8:9]
	v_mov_b32_e32 v174, v236
	v_add_u32_e32 v146, 0x90, v144
	v_ashrrev_i32_e32 v147, 31, v146
	v_lshl_add_u64 v[146:147], v[146:147], 2, s[8:9]
	v_mov_b32_e32 v172, v237
	v_add_u32_e32 v146, 0xa0, v144
	v_ashrrev_i32_e32 v147, 31, v146
	v_lshl_add_u64 v[146:147], v[146:147], 2, s[8:9]
	v_mov_b32_e32 v155, v238
	v_add_u32_e32 v146, 0xb0, v144
	v_ashrrev_i32_e32 v147, 31, v146
	v_lshl_add_u64 v[146:147], v[146:147], 2, s[8:9]
	v_mov_b32_e32 v153, v239
	v_ashrrev_i32_e32 v145, 4, v136
	v_cndmask_b32_e32 v151, 1.0, v171, vcc
	v_cmp_gt_u32_e32 vcc, 16, v136
	s_add_u32 s76, s10, 0x100000
	s_addc_u32 s77, s11, 0
	s_add_i32 s3, s14, -6
	v_or_b32_e32 v175, 0x800, v173
	s_cmp_lt_u32 s3, 3
	s_cselect_b64 s[12:13], -1, 0
	s_and_b64 s[16:17], s[42:43], s[12:13]
	v_cmp_gt_i32_e64 s[8:9], 2, v145
	v_cndmask_b32_e64 v142, 1.0, -1.0, vcc
	s_andn2_b64 vcc, exec, s[16:17]
	s_cmp_lg_u64 s[52:53], 0
	s_cbranch_scc0 .Lp1bq_nopf
	s_add_u32 s78, s20, 0x43000
	s_addc_u32 s79, s21, 0
	s_lshl_b32 s80, s48, 8
	s_add_i32 s80, s80, s35
	v_and_or_b32 v240, v196, 15, s80
	v_lshlrev_b32_e32 v240, 2, v240
	global_load_dword v232, v240, s[78:79]
	global_load_dword v233, v240, s[78:79] offset:64
	global_load_dword v234, v240, s[78:79] offset:128
	global_load_dword v235, v240, s[78:79] offset:192
	global_load_dword v236, v240, s[78:79] offset:512
	global_load_dword v237, v240, s[78:79] offset:576
	global_load_dword v238, v240, s[78:79] offset:640
	global_load_dword v239, v240, s[78:79] offset:704
.Lp1bq_nopf:
	v_fmamk_f32 v136, v148, 0x3a800000, v170
	v_rsq_f32_e32 v136, v136
	s_nop 0
	v_mul_f32_e32 v156, v151, v136
	v_mov_b32_e32 v136, s2
	v_bitop3_b32 v157, v173, s62, v136 bitop3:0xc8
	v_cndmask_b32_e64 v136, v157, v175, s[6:7]
	v_lshlrev_b32_e32 v136, 6, v136
	v_lshl_add_u64 v[158:159], s[76:77], 0, v[136:137]
	v_cndmask_b32_e64 v136, 0, 1, s[16:17]
	v_pk_mul_f32 v[124:125], v[124:125], v[156:157] op_sel_hi:[1,0]
	v_pk_mul_f32 v[120:121], v[120:121], v[156:157] op_sel_hi:[1,0]
	v_pk_mul_f32 v[126:127], v[126:127], v[156:157] op_sel_hi:[1,0]
	v_pk_mul_f32 v[122:123], v[122:123], v[156:157] op_sel_hi:[1,0]
	v_cmp_ne_u32_e64 s[12:13], 1, v136
	s_cbranch_vccnz .LBB0_910
	ds_bpermute_b32 v160, v197, v124
	ds_bpermute_b32 v161, v197, v125
	ds_bpermute_b32 v148, v197, v126
	ds_bpermute_b32 v149, v197, v127
	ds_bpermute_b32 v146, v197, v120
	ds_bpermute_b32 v147, v197, v121
	ds_bpermute_b32 v162, v197, v122
	ds_bpermute_b32 v136, v197, v123
	s_and_saveexec_b64 s[16:17], s[8:9]
	s_cbranch_execz .LBB0_909
	global_load_dwordx4 v[180:183], v[158:159], off offset:48
	global_load_dwordx4 v[184:187], v[158:159], off offset:32
	global_load_dwordx4 v[188:191], v[158:159], off offset:16
	global_load_dwordx4 v[192:195], v[158:159], off
	s_waitcnt lgkmcnt(1)
	v_mul_f32_e32 v162, v142, v162
	v_pk_mul_f32 v[160:161], v[142:143], v[160:161] op_sel_hi:[0,1]
	v_pk_mul_f32 v[148:149], v[142:143], v[148:149] op_sel_hi:[0,1]
	v_pk_mul_f32 v[146:147], v[142:143], v[146:147] op_sel_hi:[0,1]
	s_waitcnt vmcnt(3)
	v_mul_f32_e32 v122, v122, v180
	v_mul_f32_e32 v162, v162, v181
	s_waitcnt vmcnt(0)
	v_mov_b32_e32 v164, v192
	v_mov_b32_e32 v165, v194
	v_pk_mul_f32 v[124:125], v[124:125], v[164:165]
	v_mov_b32_e32 v164, v188
	v_mov_b32_e32 v165, v190
	v_pk_mul_f32 v[126:127], v[126:127], v[164:165]
	v_mov_b32_e32 v164, v184
	v_mov_b32_e32 v165, v186
	v_pk_mul_f32 v[120:121], v[120:121], v[164:165]
	s_waitcnt lgkmcnt(0)
	v_mul_f32_e32 v165, v142, v136
	v_mov_b32_e32 v164, v123
	v_pk_mul_f32 v[164:165], v[164:165], v[182:183]
	v_mov_b32_e32 v194, v193
	v_mov_b32_e32 v190, v189
	v_mov_b32_e32 v186, v185
	v_mov_b32_e32 v123, v165
	v_mov_b32_e32 v163, v164
	v_pk_fma_f32 v[124:125], v[160:161], v[194:195], v[124:125]
	v_pk_fma_f32 v[126:127], v[148:149], v[190:191], v[126:127]
	v_pk_fma_f32 v[120:121], v[146:147], v[186:187], v[120:121]
	v_pk_add_f32 v[122:123], v[122:123], v[162:163]

; __device__ __forceinline__ int lane_id() { int l = __builtin_amdgcn_mbcnt_hi(~0u, __builtin_amdgcn_mbcnt_lo(~0u, 0u)); asm volatile("" : "+v"(l)); return l; }
; #define PG8_BAR __builtin_amdgcn_s_barrier()
; template <int KK, class Epi, class Sched, bool ALIGN_EPI = true>
; __device__ __forceinline__ void gemm_phase(LAS unsigned char* lds, const bf16* gA, const bf16* gBt, const Sched& S, const Epi& E, const int wid) {
;     const int lane = lane_id();
;     const int tid = wid * 64 + lane, wr = wid >> 2, wc = wid & 3, fr = lane & 15, fq = lane >> 4;
;     constexpr int K = KK, nt = K / BK;
;     unsigned voffA[2], voffB[2];
; #pragma unroll
;     for (int i = 0; i < 2; ++i) { int R, C; stage_rc(tid * 16 + i * 8192, R, C); const int Rb = Epi::PERM ? ((R & ~31) + perm32(R & 31)) : R;
;         voffA[i] = (unsigned)(R * K + C) * 2u; voffB[i] = (unsigned)(Rb * K + C) * 2u; }
;     const size_t kstep = (size_t)(BK * 2);
;     const size_t hstep = (size_t)HALF * K * 2;
;     const size_t tstep = 2 * hstep;
;     const unsigned ldsw = (unsigned)wid * 1024u;
;     const int aoff = lds_byte(wr * 64 + fr, fq * 8), boff = lds_byte(wc * 32 + fr, fq * 8);
;     ...
;     Unit cur, nxt; int ui = 0;
;     if (!S.next(0, cur)) return;
;     f32x4 acc[2][2][4][2];
; #pragma unroll
;     for (int a = 0; a < 2; ++a)
; #pragma unroll
;         for (int b = 0; b < 2; ++b)
; #pragma unroll
;             for (int m = 0; m < 4; ++m)
; #pragma unroll
;                 for (int n = 0; n < 2; ++n) acc[a][b][m][n] = (f32x4){0.f, 0.f, 0.f, 0.f};
;     bf16x8 At[4][2], B0[2][2], B1[2][2];
;     const char* cA = (const char*)gA + (size_t)cur.pm * tstep; const char* cB = (const char*)gBt + (size_t)cur.pn * tstep;
;     PG8_STAGE(PG8_SB(0, 0), cB, voffB); PG8_STAGE(PG8_SB(0, 1), cB + hstep, voffB); PG8_STAGE(PG8_SA(0, 0), cA, voffA); PG8_STAGE(PG8_SA(0, 1), cA + hstep, voffA);
;     PG8_STAGE(PG8_SB(1, 0), cB + kstep, voffB); PG8_STAGE(PG8_SA(1, 0), cA + kstep, voffA); PG8_STAGE(PG8_SB(1, 1), cB + hstep + kstep, voffB);
;     if (wr == 1) PG8_BAR;
;     __device__ __forceinline__ void operator()(AccRef acc, const pg8::Unit& u, int wr, int wc, int, int) const {
;     ...
;             for (int m = 0; m < 4; ++m) sq[ai][m] = ssq[u.pm * 256 + ai * 128 + wr * 64 + m * 16 + fr];
.LBB0_1235:
	s_add_u32 s82, s20, 0x64000
	s_addc_u32 s83, s21, 0
	s_lshl_b32 s84, s38, 8
	s_add_i32 s84, s84, s35
	v_and_or_b32 v232, v196, 15, s84
	v_lshlrev_b32_e32 v232, 2, v232
	global_load_dword v224, v232, s[82:83]
	global_load_dword v225, v232, s[82:83] offset:64
	global_load_dword v226, v232, s[82:83] offset:128
	global_load_dword v227, v232, s[82:83] offset:192
	global_load_dword v228, v232, s[82:83] offset:512
	global_load_dword v229, v232, s[82:83] offset:576
	global_load_dword v230, v232, s[82:83] offset:640
	global_load_dword v231, v232, s[82:83] offset:704
	v_lshl_add_u32 v4, v0, 4, s33
	v_ashrrev_i32_e32 v1, 31, v4
	v_lshrrev_b32_e32 v1, 22, v1
	v_add_u32_e32 v1, v4, v1
	v_ashrrev_i32_e32 v1, 10, v1
	v_mul_i32_i24_e32 v2, 0x400, v1
	v_sub_u32_e32 v2, v4, v2
	v_lshrrev_b32_e32 v3, 4, v2
	v_bitop3_b32 v3, v3, v2, 32 bitop3:0x6c
	v_lshlrev_b32_e32 v2, 3, v1
	v_and_b32_e32 v5, -16, v2
	v_ashrrev_i32_e32 v2, 31, v3
	v_lshrrev_b32_e32 v2, 26, v2
	v_add_u32_e32 v6, v3, v2
	v_ashrrev_i32_e32 v2, 6, v6
	v_and_b32_e32 v6, 0xc0, v6
	v_sub_u32_e32 v3, v3, v6
	v_mov_b32_e32 v6, 1
	v_lshlrev_b32_e32 v7, 5, v1
	v_ashrrev_i16_sdwa v3, v6, sext(v3) dst_sel:DWORD dst_unused:UNUSED_PAD src0_sel:DWORD src1_sel:BYTE_0
	v_and_b32_e32 v7, 32, v7
	v_bfe_i32 v3, v3, 0, 16
	v_add_u32_e32 v5, v2, v5
	v_and_b32_e32 v10, 3, v2
	s_mov_b32 s6, 0x1fffe0
	v_add_lshl_u32 v7, v7, v3, 1
	v_lshlrev_b32_e32 v8, 1, v5
	v_lshrrev_b32_e32 v9, 2, v5
	v_and_or_b32 v10, v5, s6, v10
	v_lshl_add_u32 v128, v5, 11, v7
	v_add_u32_e32 v5, 0x2000, v4
	v_ashrrev_i32_e32 v4, 31, v5
	v_lshrrev_b32_e32 v4, 22, v4
	v_and_b32_e32 v8, 24, v8
	v_and_b32_e32 v9, 4, v9
	v_add_u32_e32 v4, v5, v4
	v_or3_b32 v8, v10, v9, v8
	v_ashrrev_i32_e32 v4, 10, v4
	v_lshl_add_u32 v130, v8, 11, v7
	v_mul_i32_i24_e32 v7, 0x400, v4
	v_sub_u32_e32 v5, v5, v7
	v_lshrrev_b32_e32 v7, 4, v5
	v_bitop3_b32 v7, v7, v5, 32 bitop3:0x6c
	v_lshlrev_b32_e32 v5, 3, v4
	v_and_b32_e32 v8, -16, v5
	v_ashrrev_i32_e32 v5, 31, v7
	v_lshrrev_b32_e32 v5, 26, v5
	v_add_u32_e32 v9, v7, v5
	v_ashrrev_i32_e32 v5, 6, v9
	v_and_b32_e32 v9, 0xffc0, v9
	s_add_u32 s2, s20, 0x2200000
	v_sub_u32_e32 v7, v7, v9
	s_addc_u32 s3, s21, 0
	v_add_u32_e32 v8, v5, v8
	v_lshrrev_b16_e32 v9, 7, v7
	v_and_b32_e32 v11, 3, v5
	s_ashr_i32 s39, s38, 31
	s_ashr_i32 s37, s36, 31
	v_and_b32_e32 v9, 1, v9
	v_and_or_b32 v11, v8, s6, v11
	s_lshl_b64 s[6:7], s[38:39], 19
	s_lshl_b64 s[8:9], s[36:37], 19
	v_add_u16_e32 v7, v7, v9
	s_add_u32 s42, s2, s8
	v_lshlrev_b32_e32 v10, 5, v4
	v_ashrrev_i16_sdwa v6, v6, sext(v7) dst_sel:DWORD dst_unused:UNUSED_PAD src0_sel:DWORD src1_sel:BYTE_0
	v_lshlrev_b32_e32 v7, 1, v8
	v_lshrrev_b32_e32 v9, 2, v8
	s_addc_u32 s43, s3, s9
	s_add_i32 s18, s33, 0
	v_and_b32_e32 v10, 32, v10
	v_bfe_i32 v6, v6, 0, 16
	v_and_b32_e32 v7, 24, v7
	v_and_b32_e32 v9, 4, v9
	s_add_i32 m0, s18, 0x10000
	v_or3_b32 v7, v11, v9, v7
	v_add_lshl_u32 v9, v10, v6, 1
	global_load_lds_dwordx4 v130, s[42:43]
	s_add_i32 m0, s18, 0x12000
	v_lshl_add_u32 v134, v7, 11, v9
	s_add_u32 s8, s42, 0x40000
	global_load_lds_dwordx4 v134, s[42:43]
	s_addc_u32 s9, s43, 0
	s_add_i32 m0, s18, 0x14000
	v_lshl_add_u32 v132, v8, 11, v9
	global_load_lds_dwordx4 v130, s[8:9]
	s_add_i32 m0, s18, 0x16000
	s_add_u32 s44, s4, s6
	s_addc_u32 s45, s56, s7
	s_add_i32 s19, s18, 0x2000
	global_load_lds_dwordx4 v134, s[8:9]
	s_mov_b32 m0, s18
	s_add_u32 s6, s44, 0x40000
	global_load_lds_dwordx4 v128, s[44:45]
	s_mov_b32 m0, s19
	s_addc_u32 s7, s45, 0
	s_add_i32 s37, s18, 0x4000
	global_load_lds_dwordx4 v132, s[44:45]
	s_mov_b32 m0, s37
	s_add_i32 s39, s18, 0x6000
	v_mov_b32_e32 v131, 0
	global_load_lds_dwordx4 v128, s[6:7]
	s_mov_b32 m0, s39
	v_lshl_add_u64 v[8:9], s[42:43], 0, v[130:131]
	v_mov_b32_e32 v135, v131
	global_load_lds_dwordx4 v132, s[6:7]
	s_mov_b64 s[6:7], 0x80
	v_lshl_add_u64 v[10:11], s[42:43], 0, v[134:135]
	v_mov_b32_e32 v129, v131
	s_add_i32 m0, s18, 0x18000
	v_lshl_add_u64 v[8:9], v[8:9], 0, s[6:7]
	v_lshl_add_u64 v[12:13], s[44:45], 0, v[128:129]
	v_mov_b32_e32 v133, v131
	global_load_lds_dwordx4 v[8:9], off
	v_lshl_add_u64 v[8:9], v[10:11], 0, s[6:7]
	s_add_i32 m0, s18, 0x1a000
	s_add_i32 s40, s18, 0x8000
	v_lshl_add_u64 v[14:15], s[44:45], 0, v[132:133]
	global_load_lds_dwordx4 v[8:9], off
	v_lshl_add_u64 v[8:9], v[12:13], 0, s[6:7]
	s_mov_b32 m0, s40
	s_add_i32 s41, s18, 0xa000
	global_load_lds_dwordx4 v[8:9], off
	v_lshl_add_u64 v[8:9], v[14:15], 0, s[6:7]
	s_mov_b32 m0, s41
	s_add_u32 s8, s42, 0x40080
	global_load_lds_dwordx4 v[8:9], off
	s_addc_u32 s9, s43, 0
	s_add_i32 m0, s18, 0x1c000
	v_readlane_b32 s10, v249, 42
	global_load_lds_dwordx4 v130, s[8:9]
	s_add_i32 m0, s18, 0x1e000
	s_cmp_eq_u32 s10, 1
	global_load_lds_dwordx4 v134, s[8:9]
	s_cselect_b64 s[8:9], -1, 0
	s_cmp_lg_u32 s10, 1
	s_mov_b32 s48, 0
	s_cbranch_scc1 .LBB0_1237
	s_barrier

; __device__ __forceinline__ float fexp2(float x) { return __builtin_amdgcn_exp2f(x); }
; __device__ __forceinline__ float frcp(float x) { return __builtin_amdgcn_rcpf(x); }
;     __device__ __forceinline__ void operator()(AccRef acc, const pg8::Unit& u, int wr, int wc, int, int) const {
;     ...
;         float sq[2][4];
; #pragma unroll
;         for (int ai = 0; ai < 2; ++ai)
; #pragma unroll
;             for (int m = 0; m < 4; ++m) sq[ai][m] = ssq[u.pm * 256 + ai * 128 + wr * 64 + m * 16 + fr];
;         asm volatile("" ::: "memory");
; #pragma unroll
;         for (int ai = 0; ai < 2; ++ai)
; #pragma unroll
;             for (int m = 0; m < 4; ++m) {
;                 const int row = u.pm * 256 + ai * 128 + wr * 64 + m * 16 + fr;
;                 const float rstd = __builtin_amdgcn_rsqf(sq[ai][m] * (1.0f / DM) + EPS);
;                 const float rc = -rstd * LOG2E, r2 = rstd * rstd;
;                 unsigned pk[4];
; #pragma unroll
;                 for (int n = 0; n < 2; ++n)
; #pragma unroll
;                     for (int h = 0; h < 2; ++h) {
;                         const f32x2 g2 = {acc[ai][0][m][n][2 * h], acc[ai][0][m][n][2 * h + 1]}, u2 = {acc[ai][1][m][n][2 * h], acc[ai][1][m][n][2 * h + 1]};
;                         const f32x2 x2 = g2 * rc; f32x2 d2; d2.x = fexp2(x2.x); d2.y = fexp2(x2.y); d2 = d2 + 1.0f;
;                         f32x2 q2; q2.x = frcp(d2.x); q2.y = frcp(d2.y);
.LBB0_1249:
	s_mov_b64 s[44:45], s[20:21]
	s_mov_b64 s[42:43], s[22:23]
	s_add_u32 s42, s44, 0x64000
	s_addc_u32 s43, s45, 0
	s_lshl_b32 s15, s38, 8
	v_mov_b32_e32 v142, v196
	s_add_i32 s15, s15, s35
	v_pk_mul_f32 v[162:163], v[112:113], v[120:121]
	v_and_or_b32 v154, v142, 15, s15
	v_ashrrev_i32_e32 v155, 31, v154
	v_lshl_add_u64 v[140:141], v[154:155], 2, s[42:43]
	v_mov_b32_e32 v155, v224
	v_or_b32_e32 v144, 16, v154
	v_ashrrev_i32_e32 v145, 31, v144
	v_lshl_add_u64 v[140:141], v[144:145], 2, s[42:43]
	v_mov_b32_e32 v145, v225
	v_ashrrev_i32_e32 v120, 1, v142
	v_or_b32_e32 v146, 32, v154
	v_pk_mul_f32 v[156:157], v[118:119], v[126:127]
	v_pk_mul_f32 v[158:159], v[116:117], v[124:125]
	v_pk_mul_f32 v[160:161], v[114:115], v[122:123]
	v_and_b32_e32 v122, -8, v120
	v_or_b32_e32 v142, 48, v154
	v_add_u32_e32 v140, 0x80, v154
	v_add_u32_e32 v126, 0x90, v154
	v_add_u32_e32 v124, 0xa0, v154
	v_add_u32_e32 v120, 0xb0, v154
	v_ashrrev_i32_e32 v147, 31, v146
	v_ashrrev_i32_e32 v143, 31, v142
	v_ashrrev_i32_e32 v141, 31, v140
	v_ashrrev_i32_e32 v127, 31, v126
	v_ashrrev_i32_e32 v125, 31, v124
	v_ashrrev_i32_e32 v121, 31, v120
	v_lshl_add_u64 v[164:165], v[146:147], 2, s[42:43]
	v_lshl_add_u64 v[166:167], v[142:143], 2, s[42:43]
	v_lshl_add_u64 v[168:169], v[140:141], 2, s[42:43]
	v_lshl_add_u64 v[170:171], v[126:127], 2, s[42:43]
	v_lshl_add_u64 v[172:173], v[124:125], 2, s[42:43]
	v_lshl_add_u64 v[174:175], v[120:121], 2, s[42:43]
	v_mov_b32_e32 v127, v226
	v_mov_b32_e32 v141, v227
	v_mov_b32_e32 v143, v228
	v_mov_b32_e32 v147, v229
	v_mov_b32_e32 v125, v230
	v_mov_b32_e32 v121, v231
	s_lshl_b32 s46, s36, 7
	s_ashr_i32 s47, s46, 31
	s_lshl_b64 s[46:47], s[46:47], 1
	s_add_u32 s15, s44, s46
	s_addc_u32 s17, s45, s47
	s_add_u32 s42, s15, s53
	v_pk_mul_f32 v[104:105], v[108:109], v[104:105]
	v_ashrrev_i32_e32 v123, 31, v122
	s_addc_u32 s43, s17, 0
	v_lshl_add_u64 v[122:123], v[122:123], 1, s[42:43]
	v_lshl_add_u64 v[122:123], v[122:123], 0, s[12:13]
	v_pk_mul_f32 v[106:107], v[110:111], v[106:107]
	v_pk_mul_f32 v[96:97], v[100:101], v[96:97]
	v_pk_mul_f32 v[98:99], v[102:103], v[98:99]
	v_pk_mul_f32 v[88:89], v[92:93], v[88:89]
	v_pk_mul_f32 v[90:91], v[94:95], v[90:91]
	v_pk_mul_f32 v[80:81], v[84:85], v[80:81]
	v_pk_mul_f32 v[82:83], v[86:87], v[82:83]
	v_pk_mul_f32 v[72:73], v[76:77], v[72:73]
	v_pk_mul_f32 v[74:75], v[78:79], v[74:75]
	v_pk_mul_f32 v[64:65], v[68:69], v[64:65]
	v_pk_mul_f32 v[66:67], v[70:71], v[66:67]
	v_pk_mul_f32 v[56:57], v[60:61], v[56:57]
	v_pk_mul_f32 v[58:59], v[62:63], v[58:59]
	v_pk_mul_f32 v[48:49], v[52:53], v[48:49]
	v_pk_mul_f32 v[50:51], v[54:55], v[50:51]
	v_pk_mul_f32 v[40:41], v[44:45], v[40:41]
	v_pk_mul_f32 v[42:43], v[46:47], v[42:43]
	v_pk_mul_f32 v[32:33], v[36:37], v[32:33]
	v_pk_mul_f32 v[34:35], v[38:39], v[34:35]
	v_pk_mul_f32 v[24:25], v[28:29], v[24:25]
	v_pk_mul_f32 v[26:27], v[30:31], v[26:27]
	v_pk_mul_f32 v[16:17], v[20:21], v[16:17]
	v_pk_mul_f32 v[18:19], v[22:23], v[18:19]
	v_pk_mul_f32 v[8:9], v[12:13], v[8:9]
	v_pk_mul_f32 v[10:11], v[14:15], v[10:11]
	v_pk_mul_f32 v[0:1], v[4:5], v[0:1]
	v_pk_mul_f32 v[2:3], v[6:7], v[2:3]
	s_cmp_lg_u64 s[24:25], 0
	s_cbranch_scc0 .Lp4bq_nopf
	s_add_u32 s82, s20, 0x64000
	s_addc_u32 s83, s21, 0
	s_lshl_b32 s84, s14, 8
	s_add_i32 s84, s84, s35
	v_and_or_b32 v232, v196, 15, s84
	v_lshlrev_b32_e32 v232, 2, v232
	global_load_dword v224, v232, s[82:83]
	global_load_dword v225, v232, s[82:83] offset:64
	global_load_dword v226, v232, s[82:83] offset:128
	global_load_dword v227, v232, s[82:83] offset:192
	global_load_dword v228, v232, s[82:83] offset:512
	global_load_dword v229, v232, s[82:83] offset:576
	global_load_dword v230, v232, s[82:83] offset:640
	global_load_dword v231, v232, s[82:83] offset:704
.Lp4bq_nopf:
	s_andn2_b64 vcc, exec, s[24:25]
	s_mov_b64 s[24:25], -1
	v_fmamk_f32 v155, v155, 0x3a800000, v153
	v_rsq_f32_e32 v165, v155
	v_mad_i64_i32 v[154:155], s[42:43], v154, s54, v[122:123]
	v_fmamk_f32 v145, v145, 0x3a800000, v153
	v_mul_f32_e32 v164, 0xbfb8aa3b, v165
	v_pk_mul_f32 v[116:117], v[116:117], v[164:165] op_sel_hi:[1,0]
	v_pk_mul_f32 v[118:119], v[118:119], v[164:165] op_sel_hi:[1,0]
	v_pk_mul_f32 v[112:113], v[112:113], v[164:165] op_sel_hi:[1,0]
	v_pk_mul_f32 v[114:115], v[114:115], v[164:165] op_sel_hi:[1,0]
	v_rsq_f32_e32 v145, v145
	v_exp_f32_e32 v116, v116
	v_exp_f32_e32 v117, v117
	v_exp_f32_e32 v118, v118
	v_exp_f32_e32 v119, v119
	v_exp_f32_e32 v112, v112
	v_exp_f32_e32 v113, v113
	v_exp_f32_e32 v114, v114
	v_exp_f32_e32 v115, v115
	v_mul_f32_e32 v166, v165, v165
	v_mul_f32_e32 v164, 0xbfb8aa3b, v145
	v_pk_add_f32 v[116:117], v[116:117], 1.0 op_sel_hi:[1,0]
	v_pk_add_f32 v[118:119], v[118:119], 1.0 op_sel_hi:[1,0]
	v_pk_add_f32 v[112:113], v[112:113], 1.0 op_sel_hi:[1,0]
	v_pk_add_f32 v[114:115], v[114:115], 1.0 op_sel_hi:[1,0]
	v_pk_mul_f32 v[158:159], v[158:159], v[166:167] op_sel_hi:[1,0]
	v_pk_mul_f32 v[156:157], v[156:157], v[166:167] op_sel_hi:[1,0]
	v_pk_mul_f32 v[162:163], v[162:163], v[166:167] op_sel_hi:[1,0]
	v_pk_mul_f32 v[160:161], v[160:161], v[166:167] op_sel_hi:[1,0]
	v_pk_mul_f32 v[166:167], v[108:109], v[164:165] op_sel_hi:[1,0]
	v_rcp_f32_e32 v116, v116
	v_rcp_f32_e32 v117, v117
	v_rcp_f32_e32 v118, v118
	v_rcp_f32_e32 v119, v119
	v_rcp_f32_e32 v112, v112
	v_rcp_f32_e32 v113, v113
	v_rcp_f32_e32 v114, v114
	v_rcp_f32_e32 v115, v115
	v_pk_mul_f32 v[108:109], v[110:111], v[164:165] op_sel_hi:[1,0]
	v_exp_f32_e32 v166, v166
	v_exp_f32_e32 v167, v167
	v_exp_f32_e32 v108, v108
	v_exp_f32_e32 v109, v109
	v_pk_mul_f32 v[116:117], v[158:159], v[116:117]
	v_pk_mul_f32 v[118:119], v[156:157], v[118:119]
; __device__ __forceinline__ unsigned cvt_pk(float lo, float hi) { unsigned r; asm("v_cvt_pk_bf16_f32 %0, %1, %2" : "=v"(r) : "v"(lo), "v"(hi)); return r; }
; __device__ __forceinline__ float fexp2(float x) { return __builtin_amdgcn_exp2f(x); }
; __device__ __forceinline__ float frcp(float x) { return __builtin_amdgcn_rcpf(x); }
;     __device__ __forceinline__ void operator()(AccRef acc, const pg8::Unit& u, int wr, int wc, int, int) const {
;     ...
;         for (int ai = 0; ai < 2; ++ai)
; #pragma unroll
;             for (int m = 0; m < 4; ++m) {
;                 const int row = u.pm * 256 + ai * 128 + wr * 64 + m * 16 + fr;
;                 const float rstd = __builtin_amdgcn_rsqf(sq[ai][m] * (1.0f / DM) + EPS);
;                 const float rc = -rstd * LOG2E, r2 = rstd * rstd;
;                 unsigned pk[4];
; #pragma unroll
;                 for (int n = 0; n < 2; ++n)
; #pragma unroll
;                     for (int h = 0; h < 2; ++h) {
;                         const f32x2 g2 = {acc[ai][0][m][n][2 * h], acc[ai][0][m][n][2 * h + 1]}, u2 = {acc[ai][1][m][n][2 * h], acc[ai][1][m][n][2 * h + 1]};
;                         const f32x2 x2 = g2 * rc; f32x2 d2; d2.x = fexp2(x2.x); d2.y = fexp2(x2.y); d2 = d2 + 1.0f;
;                         f32x2 q2; q2.x = frcp(d2.x); q2.y = frcp(d2.y);
;                         const f32x2 t2 = (g2 * u2) * r2 * q2;
;                         pk[2 * n + h] = cvt_pk(t2.x, t2.y);
;                     }
;                 v4u w; w.x = pk[0]; w.y = pk[1]; w.z = pk[2]; w.w = pk[3];
;                 *(v4u*)(ACT + (size_t)row * FF + u.pn * 128 + wc * 32 + 8 * fq) = w;
	v_pk_mul_f32 v[156:157], v[162:163], v[112:113]
	v_pk_mul_f32 v[158:159], v[160:161], v[114:115]
	v_cvt_pk_bf16_f32 v114, v156, v157
	v_cvt_pk_bf16_f32 v112, v116, v117
	v_cvt_pk_bf16_f32 v113, v118, v119
	v_pk_add_f32 v[108:109], v[108:109], 1.0 op_sel_hi:[1,0]
	v_cvt_pk_bf16_f32 v115, v158, v159
	global_store_dwordx4 v[154:155], v[112:115], off
	v_rcp_f32_e32 v108, v108
	v_rcp_f32_e32 v109, v109
	v_pk_add_f32 v[114:115], v[166:167], 1.0 op_sel_hi:[1,0]
	v_pk_mul_f32 v[110:111], v[100:101], v[164:165] op_sel_hi:[1,0]
	v_rcp_f32_e32 v114, v114
	v_rcp_f32_e32 v115, v115
	v_exp_f32_e32 v110, v110
	v_exp_f32_e32 v111, v111
	v_mul_f32_e32 v112, v145, v145
	v_pk_mul_f32 v[104:105], v[104:105], v[112:113] op_sel_hi:[1,0]
	v_pk_mul_f32 v[106:107], v[106:107], v[112:113] op_sel_hi:[1,0]
	v_pk_mul_f32 v[104:105], v[104:105], v[114:115]
	v_pk_mul_f32 v[106:107], v[106:107], v[108:109]
	v_cvt_pk_bf16_f32 v104, v104, v105
	v_pk_mul_f32 v[100:101], v[102:103], v[164:165] op_sel_hi:[1,0]
	v_cvt_pk_bf16_f32 v105, v106, v107
	v_pk_add_f32 v[106:107], v[110:111], 1.0 op_sel_hi:[1,0]
	v_exp_f32_e32 v100, v100
	v_rcp_f32_e32 v106, v106
	v_rcp_f32_e32 v107, v107
	v_exp_f32_e32 v101, v101
	v_pk_mul_f32 v[96:97], v[96:97], v[112:113] op_sel_hi:[1,0]
	v_pk_mul_f32 v[98:99], v[98:99], v[112:113] op_sel_hi:[1,0]
	v_pk_mul_f32 v[96:97], v[96:97], v[106:107]
	s_nop 0
	v_cvt_pk_bf16_f32 v106, v96, v97
	v_pk_add_f32 v[96:97], v[100:101], 1.0 op_sel_hi:[1,0]
	v_fmamk_f32 v100, v127, 0x3a800000, v153
	v_rcp_f32_e32 v96, v96
	v_rcp_f32_e32 v97, v97
	v_rsq_f32_e32 v102, v100
	v_mad_i64_i32 v[100:101], s[42:43], v144, s54, v[122:123]
	v_pk_mul_f32 v[96:97], v[98:99], v[96:97]
	s_nop 0
	v_cvt_pk_bf16_f32 v107, v96, v97
	v_mul_f32_e32 v96, 0xbfb8aa3b, v102
	v_pk_mul_f32 v[98:99], v[92:93], v[96:97] op_sel_hi:[1,0]
	v_pk_mul_f32 v[92:93], v[94:95], v[96:97] op_sel_hi:[1,0]
	v_exp_f32_e32 v98, v98
	v_exp_f32_e32 v99, v99
	v_exp_f32_e32 v92, v92
	v_exp_f32_e32 v93, v93
	v_pk_mul_f32 v[94:95], v[84:85], v[96:97] op_sel_hi:[1,0]
	v_pk_add_f32 v[98:99], v[98:99], 1.0 op_sel_hi:[1,0]
	v_exp_f32_e32 v94, v94
	v_pk_add_f32 v[92:93], v[92:93], 1.0 op_sel_hi:[1,0]
	v_rcp_f32_e32 v98, v98
	v_rcp_f32_e32 v99, v99
	v_rcp_f32_e32 v92, v92
	v_rcp_f32_e32 v93, v93
	v_exp_f32_e32 v95, v95
	global_store_dwordx4 v[100:101], v[104:107], off
	v_mul_f32_e32 v100, v102, v102
	v_pk_mul_f32 v[88:89], v[88:89], v[100:101] op_sel_hi:[1,0]
	v_pk_mul_f32 v[90:91], v[90:91], v[100:101] op_sel_hi:[1,0]
	v_pk_mul_f32 v[88:89], v[88:89], v[98:99]
	v_pk_mul_f32 v[90:91], v[90:91], v[92:93]
	v_cvt_pk_bf16_f32 v88, v88, v89
	v_pk_mul_f32 v[84:85], v[86:87], v[96:97] op_sel_hi:[1,0]
	v_cvt_pk_bf16_f32 v89, v90, v91
	v_pk_add_f32 v[90:91], v[94:95], 1.0 op_sel_hi:[1,0]
	v_exp_f32_e32 v84, v84
	v_rcp_f32_e32 v90, v90
	v_rcp_f32_e32 v91, v91
	v_exp_f32_e32 v85, v85
	v_pk_mul_f32 v[80:81], v[80:81], v[100:101] op_sel_hi:[1,0]
	v_pk_mul_f32 v[82:83], v[82:83], v[100:101] op_sel_hi:[1,0]
	v_pk_mul_f32 v[80:81], v[80:81], v[90:91]
	s_nop 0
	v_cvt_pk_bf16_f32 v90, v80, v81
	v_pk_add_f32 v[80:81], v[84:85], 1.0 op_sel_hi:[1,0]
	v_fmamk_f32 v84, v141, 0x3a800000, v153
	v_rcp_f32_e32 v80, v80
	v_rcp_f32_e32 v81, v81
	v_rsq_f32_e32 v86, v84
	v_mad_i64_i32 v[84:85], s[42:43], v146, s54, v[122:123]
	v_pk_mul_f32 v[80:81], v[82:83], v[80:81]
	s_nop 0
	v_cvt_pk_bf16_f32 v91, v80, v81
	v_mul_f32_e32 v80, 0xbfb8aa3b, v86
	v_pk_mul_f32 v[82:83], v[76:77], v[80:81] op_sel_hi:[1,0]
	v_pk_mul_f32 v[76:77], v[78:79], v[80:81] op_sel_hi:[1,0]
	v_exp_f32_e32 v82, v82
	v_exp_f32_e32 v83, v83
	v_exp_f32_e32 v76, v76
	v_exp_f32_e32 v77, v77
	v_pk_mul_f32 v[78:79], v[68:69], v[80:81] op_sel_hi:[1,0]
	v_pk_add_f32 v[82:83], v[82:83], 1.0 op_sel_hi:[1,0]
	v_exp_f32_e32 v78, v78
	v_pk_add_f32 v[76:77], v[76:77], 1.0 op_sel_hi:[1,0]
	v_rcp_f32_e32 v82, v82
	v_rcp_f32_e32 v83, v83
	v_rcp_f32_e32 v76, v76
	v_rcp_f32_e32 v77, v77
	v_exp_f32_e32 v79, v79
	global_store_dwordx4 v[84:85], v[88:91], off
	v_mul_f32_e32 v84, v86, v86
	v_pk_mul_f32 v[72:73], v[72:73], v[84:85] op_sel_hi:[1,0]
	v_pk_mul_f32 v[74:75], v[74:75], v[84:85] op_sel_hi:[1,0]
	v_pk_mul_f32 v[72:73], v[72:73], v[82:83]
	v_pk_mul_f32 v[74:75], v[74:75], v[76:77]
	v_cvt_pk_bf16_f32 v72, v72, v73
	v_pk_mul_f32 v[68:69], v[70:71], v[80:81] op_sel_hi:[1,0]
	v_cvt_pk_bf16_f32 v73, v74, v75
	v_pk_add_f32 v[74:75], v[78:79], 1.0 op_sel_hi:[1,0]
	v_exp_f32_e32 v68, v68
	v_rcp_f32_e32 v74, v74
	v_rcp_f32_e32 v75, v75
	v_exp_f32_e32 v69, v69
	v_pk_mul_f32 v[64:65], v[64:65], v[84:85] op_sel_hi:[1,0]
	v_pk_mul_f32 v[66:67], v[66:67], v[84:85] op_sel_hi:[1,0]
	v_pk_mul_f32 v[64:65], v[64:65], v[74:75]
	s_nop 0
	v_cvt_pk_bf16_f32 v74, v64, v65
	v_pk_add_f32 v[64:65], v[68:69], 1.0 op_sel_hi:[1,0]
	v_fmamk_f32 v68, v143, 0x3a800000, v153
	v_rcp_f32_e32 v64, v64
	v_rcp_f32_e32 v65, v65
	v_rsq_f32_e32 v70, v68
	v_mad_i64_i32 v[68:69], s[42:43], v142, s54, v[122:123]
	v_pk_mul_f32 v[64:65], v[66:67], v[64:65]
	s_nop 0
	v_cvt_pk_bf16_f32 v75, v64, v65
	v_mul_f32_e32 v64, 0xbfb8aa3b, v70
	v_pk_mul_f32 v[66:67], v[60:61], v[64:65] op_sel_hi:[1,0]
	v_pk_mul_f32 v[60:61], v[62:63], v[64:65] op_sel_hi:[1,0]
	v_exp_f32_e32 v66, v66
	v_exp_f32_e32 v67, v67
	v_exp_f32_e32 v60, v60
	v_exp_f32_e32 v61, v61
	v_pk_mul_f32 v[62:63], v[52:53], v[64:65] op_sel_hi:[1,0]
	v_pk_add_f32 v[66:67], v[66:67], 1.0 op_sel_hi:[1,0]
	v_exp_f32_e32 v62, v62
	v_pk_add_f32 v[60:61], v[60:61], 1.0 op_sel_hi:[1,0]
	v_rcp_f32_e32 v66, v66
	v_rcp_f32_e32 v67, v67
	v_rcp_f32_e32 v60, v60
	v_rcp_f32_e32 v61, v61
	v_exp_f32_e32 v63, v63
	global_store_dwordx4 v[68:69], v[72:75], off
	v_mul_f32_e32 v68, v70, v70
; __device__ __forceinline__ unsigned cvt_pk(float lo, float hi) { unsigned r; asm("v_cvt_pk_bf16_f32 %0, %1, %2" : "=v"(r) : "v"(lo), "v"(hi)); return r; }
; __device__ __forceinline__ float fexp2(float x) { return __builtin_amdgcn_exp2f(x); }
; __device__ __forceinline__ float frcp(float x) { return __builtin_amdgcn_rcpf(x); }
; template <int KK, class Epi, class Sched, bool ALIGN_EPI = true>
; __device__ __forceinline__ void gemm_phase(LAS unsigned char* lds, const bf16* gA, const bf16* gBt, const Sched& S, const Epi& E, const int wid) {
;     ...
;         if constexpr (ALIGN_EPI) { if (wr == 0) PG8_BAR; }
;         E(acc, cur, wr, wc, fr, fq);
;         if (!has_next) break;
; #pragma unroll
;         for (int a = 0; a < 2; ++a)
; #pragma unroll
;             for (int b = 0; b < 2; ++b)
; #pragma unroll
;                 for (int m = 0; m < 4; ++m)
; #pragma unroll
;                     for (int n = 0; n < 2; ++n) acc[a][b][m][n] = (f32x4){0.f, 0.f, 0.f, 0.f};
;         cur = nxt; cA = nA; cB = nB; ++ui;
;         if constexpr (ALIGN_EPI) { if (wr == 1) PG8_BAR; }
;     }
;     __device__ __forceinline__ void operator()(AccRef acc, const pg8::Unit& u, int wr, int wc, int, int) const {
;     ...
;         for (int ai = 0; ai < 2; ++ai)
; #pragma unroll
;             for (int m = 0; m < 4; ++m) {
;                 const int row = u.pm * 256 + ai * 128 + wr * 64 + m * 16 + fr;
;                 const float rstd = __builtin_amdgcn_rsqf(sq[ai][m] * (1.0f / DM) + EPS);
;                 const float rc = -rstd * LOG2E, r2 = rstd * rstd;
;                 unsigned pk[4];
; #pragma unroll
;                 for (int n = 0; n < 2; ++n)
; #pragma unroll
;                     for (int h = 0; h < 2; ++h) {
;                         const f32x2 g2 = {acc[ai][0][m][n][2 * h], acc[ai][0][m][n][2 * h + 1]}, u2 = {acc[ai][1][m][n][2 * h], acc[ai][1][m][n][2 * h + 1]};
;                         const f32x2 x2 = g2 * rc; f32x2 d2; d2.x = fexp2(x2.x); d2.y = fexp2(x2.y); d2 = d2 + 1.0f;
;                         f32x2 q2; q2.x = frcp(d2.x); q2.y = frcp(d2.y);
;                         const f32x2 t2 = (g2 * u2) * r2 * q2;
;                         pk[2 * n + h] = cvt_pk(t2.x, t2.y);
;                     }
;                 v4u w; w.x = pk[0]; w.y = pk[1]; w.z = pk[2]; w.w = pk[3];
;                 *(v4u*)(ACT + (size_t)row * FF + u.pn * 128 + wc * 32 + 8 * fq) = w;
	v_pk_mul_f32 v[56:57], v[56:57], v[68:69] op_sel_hi:[1,0]
	v_pk_mul_f32 v[58:59], v[58:59], v[68:69] op_sel_hi:[1,0]
	v_pk_mul_f32 v[56:57], v[56:57], v[66:67]
	v_pk_mul_f32 v[58:59], v[58:59], v[60:61]
	v_cvt_pk_bf16_f32 v56, v56, v57
	v_pk_mul_f32 v[52:53], v[54:55], v[64:65] op_sel_hi:[1,0]
	v_cvt_pk_bf16_f32 v57, v58, v59
	v_pk_add_f32 v[58:59], v[62:63], 1.0 op_sel_hi:[1,0]
	v_exp_f32_e32 v52, v52
	v_rcp_f32_e32 v58, v58
	v_rcp_f32_e32 v59, v59
	v_exp_f32_e32 v53, v53
	v_pk_mul_f32 v[48:49], v[48:49], v[68:69] op_sel_hi:[1,0]
	v_pk_mul_f32 v[50:51], v[50:51], v[68:69] op_sel_hi:[1,0]
	v_pk_mul_f32 v[48:49], v[48:49], v[58:59]
	s_nop 0
	v_cvt_pk_bf16_f32 v58, v48, v49
	v_pk_add_f32 v[48:49], v[52:53], 1.0 op_sel_hi:[1,0]
	v_fmamk_f32 v52, v147, 0x3a800000, v153
	v_rcp_f32_e32 v48, v48
	v_rcp_f32_e32 v49, v49
	v_rsq_f32_e32 v54, v52
	v_mad_i64_i32 v[52:53], s[42:43], v140, s54, v[122:123]
	v_pk_mul_f32 v[48:49], v[50:51], v[48:49]
	s_nop 0
	v_cvt_pk_bf16_f32 v59, v48, v49
	v_mul_f32_e32 v48, 0xbfb8aa3b, v54
	v_pk_mul_f32 v[50:51], v[44:45], v[48:49] op_sel_hi:[1,0]
	v_pk_mul_f32 v[44:45], v[46:47], v[48:49] op_sel_hi:[1,0]
	v_exp_f32_e32 v50, v50
	v_exp_f32_e32 v51, v51
	v_exp_f32_e32 v44, v44
	v_exp_f32_e32 v45, v45
	v_pk_mul_f32 v[46:47], v[36:37], v[48:49] op_sel_hi:[1,0]
	v_pk_add_f32 v[50:51], v[50:51], 1.0 op_sel_hi:[1,0]
	v_exp_f32_e32 v46, v46
	v_pk_add_f32 v[44:45], v[44:45], 1.0 op_sel_hi:[1,0]
	v_rcp_f32_e32 v50, v50
	v_rcp_f32_e32 v51, v51
	v_rcp_f32_e32 v44, v44
	v_rcp_f32_e32 v45, v45
	v_exp_f32_e32 v47, v47
	global_store_dwordx4 v[52:53], v[56:59], off
	v_mul_f32_e32 v52, v54, v54
	v_pk_mul_f32 v[40:41], v[40:41], v[52:53] op_sel_hi:[1,0]
	v_pk_mul_f32 v[42:43], v[42:43], v[52:53] op_sel_hi:[1,0]
	v_pk_mul_f32 v[40:41], v[40:41], v[50:51]
	v_pk_mul_f32 v[42:43], v[42:43], v[44:45]
	v_cvt_pk_bf16_f32 v40, v40, v41
	v_pk_mul_f32 v[36:37], v[38:39], v[48:49] op_sel_hi:[1,0]
	v_cvt_pk_bf16_f32 v41, v42, v43
	v_pk_add_f32 v[42:43], v[46:47], 1.0 op_sel_hi:[1,0]
	v_exp_f32_e32 v36, v36
	v_rcp_f32_e32 v42, v42
	v_rcp_f32_e32 v43, v43
	v_exp_f32_e32 v37, v37
	v_pk_mul_f32 v[32:33], v[32:33], v[52:53] op_sel_hi:[1,0]
	v_pk_mul_f32 v[34:35], v[34:35], v[52:53] op_sel_hi:[1,0]
	v_pk_mul_f32 v[32:33], v[32:33], v[42:43]
	s_nop 0
	v_cvt_pk_bf16_f32 v42, v32, v33
	v_pk_add_f32 v[32:33], v[36:37], 1.0 op_sel_hi:[1,0]
	v_fmamk_f32 v36, v125, 0x3a800000, v153
	v_rcp_f32_e32 v32, v32
	v_rcp_f32_e32 v33, v33
	v_rsq_f32_e32 v38, v36
	v_mad_i64_i32 v[36:37], s[42:43], v126, s54, v[122:123]
	v_pk_mul_f32 v[32:33], v[34:35], v[32:33]
	s_nop 0
	v_cvt_pk_bf16_f32 v43, v32, v33
	v_mul_f32_e32 v32, 0xbfb8aa3b, v38
	v_pk_mul_f32 v[34:35], v[28:29], v[32:33] op_sel_hi:[1,0]
	v_pk_mul_f32 v[28:29], v[30:31], v[32:33] op_sel_hi:[1,0]
	v_exp_f32_e32 v34, v34
	v_exp_f32_e32 v35, v35
	v_exp_f32_e32 v28, v28
	v_exp_f32_e32 v29, v29
	v_pk_mul_f32 v[30:31], v[20:21], v[32:33] op_sel_hi:[1,0]
	v_pk_add_f32 v[34:35], v[34:35], 1.0 op_sel_hi:[1,0]
	v_exp_f32_e32 v30, v30
	v_pk_add_f32 v[28:29], v[28:29], 1.0 op_sel_hi:[1,0]
	v_rcp_f32_e32 v34, v34
	v_rcp_f32_e32 v35, v35
	v_rcp_f32_e32 v28, v28
	v_rcp_f32_e32 v29, v29
	v_exp_f32_e32 v31, v31
	global_store_dwordx4 v[36:37], v[40:43], off
	v_mul_f32_e32 v36, v38, v38
	v_pk_mul_f32 v[24:25], v[24:25], v[36:37] op_sel_hi:[1,0]
	v_pk_mul_f32 v[26:27], v[26:27], v[36:37] op_sel_hi:[1,0]
	v_pk_mul_f32 v[24:25], v[24:25], v[34:35]
	v_pk_mul_f32 v[26:27], v[26:27], v[28:29]
	v_cvt_pk_bf16_f32 v24, v24, v25
	v_pk_mul_f32 v[20:21], v[22:23], v[32:33] op_sel_hi:[1,0]
	v_cvt_pk_bf16_f32 v25, v26, v27
	v_pk_add_f32 v[26:27], v[30:31], 1.0 op_sel_hi:[1,0]
	v_exp_f32_e32 v20, v20
	v_rcp_f32_e32 v26, v26
	v_rcp_f32_e32 v27, v27
	v_exp_f32_e32 v21, v21
	v_pk_mul_f32 v[16:17], v[16:17], v[36:37] op_sel_hi:[1,0]
	v_pk_mul_f32 v[18:19], v[18:19], v[36:37] op_sel_hi:[1,0]
	v_pk_mul_f32 v[16:17], v[16:17], v[26:27]
	s_nop 0
	v_cvt_pk_bf16_f32 v26, v16, v17
	v_pk_add_f32 v[16:17], v[20:21], 1.0 op_sel_hi:[1,0]
	v_fmamk_f32 v20, v121, 0x3a800000, v153
	v_rcp_f32_e32 v16, v16
	v_rcp_f32_e32 v17, v17
	v_rsq_f32_e32 v22, v20
	v_mad_i64_i32 v[20:21], s[42:43], v124, s54, v[122:123]
	v_pk_mul_f32 v[16:17], v[18:19], v[16:17]
	s_nop 0
	v_cvt_pk_bf16_f32 v27, v16, v17
	v_mul_f32_e32 v16, 0xbfb8aa3b, v22
	v_pk_mul_f32 v[18:19], v[12:13], v[16:17] op_sel_hi:[1,0]
	v_pk_mul_f32 v[12:13], v[14:15], v[16:17] op_sel_hi:[1,0]
	v_exp_f32_e32 v18, v18
	v_exp_f32_e32 v12, v12
	v_exp_f32_e32 v13, v13
	v_exp_f32_e32 v19, v19
	global_store_dwordx4 v[20:21], v[24:27], off
	v_mul_f32_e32 v20, v22, v22
	v_pk_add_f32 v[12:13], v[12:13], 1.0 op_sel_hi:[1,0]
	v_pk_add_f32 v[18:19], v[18:19], 1.0 op_sel_hi:[1,0]
	v_rcp_f32_e32 v12, v12
	v_rcp_f32_e32 v13, v13
	v_rcp_f32_e32 v18, v18
	v_rcp_f32_e32 v19, v19
	v_pk_mul_f32 v[14:15], v[4:5], v[16:17] op_sel_hi:[1,0]
	v_pk_mul_f32 v[10:11], v[10:11], v[20:21] op_sel_hi:[1,0]
	v_exp_f32_e32 v14, v14
	v_exp_f32_e32 v15, v15
	v_pk_mul_f32 v[10:11], v[10:11], v[12:13]
	v_pk_mul_f32 v[12:13], v[6:7], v[16:17] op_sel_hi:[1,0]
	v_pk_mul_f32 v[8:9], v[8:9], v[20:21] op_sel_hi:[1,0]
	v_exp_f32_e32 v12, v12
	v_exp_f32_e32 v13, v13
	v_pk_mul_f32 v[8:9], v[8:9], v[18:19]
	v_pk_mul_f32 v[0:1], v[0:1], v[20:21] op_sel_hi:[1,0]
	v_cvt_pk_bf16_f32 v8, v8, v9
	v_cvt_pk_bf16_f32 v9, v10, v11
	v_pk_add_f32 v[10:11], v[14:15], 1.0 op_sel_hi:[1,0]
	v_pk_add_f32 v[4:5], v[12:13], 1.0 op_sel_hi:[1,0]
	v_rcp_f32_e32 v10, v10
	v_rcp_f32_e32 v11, v11
	v_rcp_f32_e32 v4, v4
	v_rcp_f32_e32 v5, v5
	v_pk_mul_f32 v[0:1], v[0:1], v[10:11]
	s_nop 0
	v_cvt_pk_bf16_f32 v10, v0, v1
	v_pk_mul_f32 v[0:1], v[2:3], v[20:21] op_sel_hi:[1,0]
	s_nop 0
	v_pk_mul_f32 v[0:1], v[0:1], v[4:5]
	s_nop 0
	v_cvt_pk_bf16_f32 v11, v0, v1
	v_mad_i64_i32 v[0:1], s[42:43], v120, s54, v[122:123]
	global_store_dwordx4 v[0:1], v[8:11], off
	s_cbranch_vccnz .LBB0_1239
	s_andn2_b64 vcc, exec, s[8:9]
	s_cbranch_vccnz .LBB0_1238
	s_barrier
	s_branch .LBB0_1238
